# code placement: the 15 GEMM K-loop heads aligned to 64 bytes
# baseline (speedup 1.0000x reference)
; template <class Epi, class Sched, bool ALIGN_EPI = true, bool SP2 = true>
; __device__ __forceinline__ void gemm_phase(LAS unsigned char* lds, const bf16_t* Ag, const bf16_t* Btg, const int K, const int lda, const int ldb, const Sched& S, const Epi& E) {
;     ...
;         const bool has_next = S.next(ui + 1, nxt);
;         const char* nA = has_next ? (const char*)Ag + nxt.aoff : cA; const char* nB = has_next ? (const char*)Btg + nxt.boff : cB;
;     ...
; #pragma unroll
;         for (int a = 0; a < 2; ++a)
; #pragma unroll
;             for (int b = 0; b < 2; ++b)
; #pragma unroll
;                 for (int m = 0; m < 4; ++m)
; #pragma unroll
;                     for (int n = 0; n < 2; ++n) acc[a][b][m][n] = (f32x4){0.f, 0.f, 0.f, 0.f};
;         cur = nxt; cA = nA; cB = nB; ++ui;
.LBB0_118:
	s_add_u32 s26, s80, s20
	s_addc_u32 s27, s81, s21
	s_and_b64 s[6:7], s[2:3], exec
	s_cselect_b32 s8, s27, s35
	s_cselect_b32 s9, s26, s34
	s_add_u32 s28, s12, s22
	s_addc_u32 s29, s13, s23
	s_and_b64 s[6:7], s[2:3], exec
	s_cselect_b32 s33, s29, s39
	s_cselect_b32 s6, s28, s38
	s_add_u32 s34, s34, 0x80080
	s_addc_u32 s35, s35, 0
	s_add_u32 s7, s38, 0x100
	v_mov_b32_e32 v0, 0
	s_addc_u32 s59, s39, 0
	s_mov_b32 s60, -2
	v_mov_b32_e32 v1, v0
	v_mov_b32_e32 v2, v0
	v_mov_b32_e32 v3, v0
	v_mov_b32_e32 v8, v0
	v_mov_b32_e32 v9, v0
	v_mov_b32_e32 v10, v0
	v_mov_b32_e32 v11, v0
	v_mov_b32_e32 v16, v0
	v_mov_b32_e32 v17, v0
	v_mov_b32_e32 v18, v0
	v_mov_b32_e32 v19, v0
	v_mov_b32_e32 v24, v0
	v_mov_b32_e32 v25, v0
	v_mov_b32_e32 v26, v0
	v_mov_b32_e32 v27, v0
	v_mov_b32_e32 v32, v0
	v_mov_b32_e32 v33, v0
	v_mov_b32_e32 v34, v0
	v_mov_b32_e32 v35, v0
	v_mov_b32_e32 v40, v0
	v_mov_b32_e32 v41, v0
	v_mov_b32_e32 v42, v0
	v_mov_b32_e32 v43, v0
	v_mov_b32_e32 v48, v0
	v_mov_b32_e32 v49, v0
	v_mov_b32_e32 v50, v0
	v_mov_b32_e32 v51, v0
	v_mov_b32_e32 v56, v0
	v_mov_b32_e32 v57, v0
	v_mov_b32_e32 v58, v0
	v_mov_b32_e32 v59, v0
	v_mov_b32_e32 v4, v0
	v_mov_b32_e32 v5, v0
	v_mov_b32_e32 v6, v0
	v_mov_b32_e32 v7, v0
	v_mov_b32_e32 v12, v0
	v_mov_b32_e32 v13, v0
	v_mov_b32_e32 v14, v0
	v_mov_b32_e32 v15, v0
	v_mov_b32_e32 v20, v0
	v_mov_b32_e32 v21, v0
	v_mov_b32_e32 v22, v0
	v_mov_b32_e32 v23, v0
	v_mov_b32_e32 v28, v0
	v_mov_b32_e32 v29, v0
	v_mov_b32_e32 v30, v0
	v_mov_b32_e32 v31, v0
	v_mov_b32_e32 v36, v0
	v_mov_b32_e32 v37, v0
	v_mov_b32_e32 v38, v0
	v_mov_b32_e32 v39, v0
	v_mov_b32_e32 v44, v0
	v_mov_b32_e32 v45, v0
	v_mov_b32_e32 v46, v0
	v_mov_b32_e32 v47, v0
	v_mov_b32_e32 v52, v0
	v_mov_b32_e32 v53, v0
	v_mov_b32_e32 v54, v0
	v_mov_b32_e32 v55, v0
	v_mov_b32_e32 v60, v0
	v_mov_b32_e32 v61, v0
	v_mov_b32_e32 v62, v0
	v_mov_b32_e32 v63, v0
	v_mov_b32_e32 v64, v0
	v_mov_b32_e32 v65, v0
	v_mov_b32_e32 v66, v0
	v_mov_b32_e32 v67, v0
	v_mov_b32_e32 v72, v0
	v_mov_b32_e32 v73, v0
	v_mov_b32_e32 v74, v0
	v_mov_b32_e32 v75, v0
	v_mov_b32_e32 v80, v0
	v_mov_b32_e32 v81, v0
	v_mov_b32_e32 v82, v0
	v_mov_b32_e32 v83, v0
	v_mov_b32_e32 v88, v0
	v_mov_b32_e32 v89, v0
	v_mov_b32_e32 v90, v0
	v_mov_b32_e32 v91, v0
	v_mov_b32_e32 v96, v0
	v_mov_b32_e32 v97, v0
	v_mov_b32_e32 v98, v0
	v_mov_b32_e32 v99, v0
	v_mov_b32_e32 v104, v0
	v_mov_b32_e32 v105, v0
	v_mov_b32_e32 v106, v0
	v_mov_b32_e32 v107, v0
	v_mov_b32_e32 v112, v0
	v_mov_b32_e32 v113, v0
	v_mov_b32_e32 v114, v0
	v_mov_b32_e32 v115, v0
	v_mov_b32_e32 v120, v0
	v_mov_b32_e32 v121, v0
	v_mov_b32_e32 v122, v0
	v_mov_b32_e32 v123, v0
	v_mov_b32_e32 v68, v0
	v_mov_b32_e32 v69, v0
	v_mov_b32_e32 v70, v0
	v_mov_b32_e32 v71, v0
	v_mov_b32_e32 v76, v0
	v_mov_b32_e32 v77, v0
	v_mov_b32_e32 v78, v0
	v_mov_b32_e32 v79, v0
	v_mov_b32_e32 v84, v0
	v_mov_b32_e32 v85, v0
	v_mov_b32_e32 v86, v0
	v_mov_b32_e32 v87, v0
	v_mov_b32_e32 v92, v0
	v_mov_b32_e32 v93, v0
	v_mov_b32_e32 v94, v0
	v_mov_b32_e32 v95, v0
	v_mov_b32_e32 v100, v0
	v_mov_b32_e32 v101, v0
	v_mov_b32_e32 v102, v0
	v_mov_b32_e32 v103, v0
	v_mov_b32_e32 v108, v0
	v_mov_b32_e32 v109, v0
	v_mov_b32_e32 v110, v0
	v_mov_b32_e32 v111, v0
	v_mov_b32_e32 v116, v0
	v_mov_b32_e32 v117, v0
	v_mov_b32_e32 v118, v0
	v_mov_b32_e32 v119, v0
	v_mov_b32_e32 v124, v0
	v_mov_b32_e32 v125, v0
	v_mov_b32_e32 v126, v0
	v_mov_b32_e32 v127, v0
	.p2align	6

; template <class Epi, class Sched, bool ALIGN_EPI = true, bool SP2 = true>
; __device__ __forceinline__ void gemm_phase(LAS unsigned char* lds, const bf16_t* Ag, const bf16_t* Btg, const int K, const int lda, const int ldb, const Sched& S, const Epi& E) {
;     ...
;         const bool has_next = S.next(ui + 1, nxt);
;         const char* nA = has_next ? (const char*)Ag + nxt.aoff : cA; const char* nB = has_next ? (const char*)Btg + nxt.boff : cB;
;     ...
; #pragma unroll
;         for (int a = 0; a < 2; ++a)
; #pragma unroll
;             for (int b = 0; b < 2; ++b)
; #pragma unroll
;                 for (int m = 0; m < 4; ++m)
; #pragma unroll
;                     for (int n = 0; n < 2; ++n) acc[a][b][m][n] = (f32x4){0.f, 0.f, 0.f, 0.f};
;         cur = nxt; cA = nA; cB = nB; ++ui;
.LBB0_198:
	v_readlane_b32 s0, v244, 11
	v_readlane_b32 s1, v244, 12
	s_add_u32 s68, s0, s60
	s_addc_u32 s69, s1, s61
	s_and_b64 s[0:1], s[2:3], exec
	s_mov_b64 s[0:1], s[42:43]
	s_cselect_b32 vcc_lo, s69, s67
	s_cselect_b32 vcc_hi, s68, s66
	s_add_u32 s56, s0, s62
	s_addc_u32 s57, s1, s63
	s_and_b64 s[0:1], s[2:3], exec
	s_cselect_b32 s6, s57, s73
	s_cselect_b32 s7, s56, s72
	s_add_u32 s84, s66, 0x160080
	s_addc_u32 s85, s67, 0
	s_add_u32 s72, s72, 0x100
	v_mov_b32_e32 v0, 0
	s_addc_u32 s73, s73, 0
	s_mov_b32 s0, -2
	v_mov_b32_e32 v1, v0
	v_mov_b32_e32 v2, v0
	v_mov_b32_e32 v3, v0
	v_mov_b32_e32 v4, v0
	v_mov_b32_e32 v5, v0
	v_mov_b32_e32 v6, v0
	v_mov_b32_e32 v7, v0
	v_mov_b32_e32 v12, v0
	v_mov_b32_e32 v13, v0
	v_mov_b32_e32 v14, v0
	v_mov_b32_e32 v15, v0
	v_mov_b32_e32 v20, v0
	v_mov_b32_e32 v21, v0
	v_mov_b32_e32 v22, v0
	v_mov_b32_e32 v23, v0
	v_mov_b32_e32 v28, v0
	v_mov_b32_e32 v29, v0
	v_mov_b32_e32 v30, v0
	v_mov_b32_e32 v31, v0
	v_mov_b32_e32 v32, v0
	v_mov_b32_e32 v33, v0
	v_mov_b32_e32 v34, v0
	v_mov_b32_e32 v35, v0
	v_mov_b32_e32 v44, v0
	v_mov_b32_e32 v45, v0
	v_mov_b32_e32 v46, v0
	v_mov_b32_e32 v47, v0
	v_mov_b32_e32 v48, v0
	v_mov_b32_e32 v49, v0
	v_mov_b32_e32 v50, v0
	v_mov_b32_e32 v51, v0
	v_mov_b32_e32 v8, v0
	v_mov_b32_e32 v9, v0
	v_mov_b32_e32 v10, v0
	v_mov_b32_e32 v11, v0
	v_mov_b32_e32 v16, v0
	v_mov_b32_e32 v17, v0
	v_mov_b32_e32 v18, v0
	v_mov_b32_e32 v19, v0
	v_mov_b32_e32 v24, v0
	v_mov_b32_e32 v25, v0
	v_mov_b32_e32 v26, v0
	v_mov_b32_e32 v27, v0
	v_mov_b32_e32 v36, v0
	v_mov_b32_e32 v37, v0
	v_mov_b32_e32 v38, v0
	v_mov_b32_e32 v39, v0
	v_mov_b32_e32 v40, v0
	v_mov_b32_e32 v41, v0
	v_mov_b32_e32 v42, v0
	v_mov_b32_e32 v43, v0
	v_mov_b32_e32 v52, v0
	v_mov_b32_e32 v53, v0
	v_mov_b32_e32 v54, v0
	v_mov_b32_e32 v55, v0
	v_mov_b32_e32 v56, v0
	v_mov_b32_e32 v57, v0
	v_mov_b32_e32 v58, v0
	v_mov_b32_e32 v59, v0
	v_mov_b32_e32 v60, v0
	v_mov_b32_e32 v61, v0
	v_mov_b32_e32 v62, v0
	v_mov_b32_e32 v63, v0
	v_mov_b32_e32 v64, v0
	v_mov_b32_e32 v65, v0
	v_mov_b32_e32 v66, v0
	v_mov_b32_e32 v67, v0
	v_mov_b32_e32 v68, v0
	v_mov_b32_e32 v69, v0
	v_mov_b32_e32 v70, v0
	v_mov_b32_e32 v71, v0
	v_mov_b32_e32 v76, v0
	v_mov_b32_e32 v77, v0
	v_mov_b32_e32 v78, v0
	v_mov_b32_e32 v79, v0
	v_mov_b32_e32 v80, v0
	v_mov_b32_e32 v81, v0
	v_mov_b32_e32 v82, v0
	v_mov_b32_e32 v83, v0
	v_mov_b32_e32 v92, v0
	v_mov_b32_e32 v93, v0
	v_mov_b32_e32 v94, v0
	v_mov_b32_e32 v95, v0
	v_mov_b32_e32 v96, v0
	v_mov_b32_e32 v97, v0
	v_mov_b32_e32 v98, v0
	v_mov_b32_e32 v99, v0
	v_mov_b32_e32 v108, v0
	v_mov_b32_e32 v109, v0
	v_mov_b32_e32 v110, v0
	v_mov_b32_e32 v111, v0
	v_mov_b32_e32 v112, v0
	v_mov_b32_e32 v113, v0
	v_mov_b32_e32 v114, v0
	v_mov_b32_e32 v115, v0
	v_mov_b32_e32 v72, v0
	v_mov_b32_e32 v73, v0
	v_mov_b32_e32 v74, v0
	v_mov_b32_e32 v75, v0
	v_mov_b32_e32 v84, v0
	v_mov_b32_e32 v85, v0
	v_mov_b32_e32 v86, v0
	v_mov_b32_e32 v87, v0
	v_mov_b32_e32 v88, v0
	v_mov_b32_e32 v89, v0
	v_mov_b32_e32 v90, v0
	v_mov_b32_e32 v91, v0
	v_mov_b32_e32 v100, v0
	v_mov_b32_e32 v101, v0
	v_mov_b32_e32 v102, v0
	v_mov_b32_e32 v103, v0
	v_mov_b32_e32 v104, v0
	v_mov_b32_e32 v105, v0
	v_mov_b32_e32 v106, v0
	v_mov_b32_e32 v107, v0
	v_mov_b32_e32 v116, v0
	v_mov_b32_e32 v117, v0
	v_mov_b32_e32 v118, v0
	v_mov_b32_e32 v119, v0
	v_mov_b32_e32 v120, v0
	v_mov_b32_e32 v121, v0
	v_mov_b32_e32 v122, v0
	v_mov_b32_e32 v123, v0
	v_mov_b32_e32 v124, v0
	v_mov_b32_e32 v125, v0
	v_mov_b32_e32 v126, v0
	v_mov_b32_e32 v127, v0
	.p2align	6

; template <class Epi, class Sched, bool ALIGN_EPI = true, bool SP2 = true>
; __device__ __forceinline__ void gemm_phase(LAS unsigned char* lds, const bf16_t* Ag, const bf16_t* Btg, const int K, const int lda, const int ldb, const Sched& S, const Epi& E) {
;     ...
;         const bool has_next = S.next(ui + 1, nxt);
;         const char* nA = has_next ? (const char*)Ag + nxt.aoff : cA; const char* nB = has_next ? (const char*)Btg + nxt.boff : cB;
;     ...
; #pragma unroll
;         for (int a = 0; a < 2; ++a)
; #pragma unroll
;             for (int b = 0; b < 2; ++b)
; #pragma unroll
;                 for (int m = 0; m < 4; ++m)
; #pragma unroll
;                     for (int n = 0; n < 2; ++n) acc[a][b][m][n] = (f32x4){0.f, 0.f, 0.f, 0.f};
;         cur = nxt; cA = nA; cB = nB; ++ui;
.LBB0_277:
	s_add_u32 s26, s37, s18
	s_addc_u32 s27, s40, s19
	s_and_b64 s[6:7], s[16:17], exec
	s_cselect_b32 s55, s27, s31
	s_cselect_b32 s56, s26, s30
	s_add_u32 s28, s76, s20
	s_addc_u32 s29, s77, s21
	s_and_b64 s[6:7], s[16:17], exec
	s_cselect_b32 s6, s29, s35
	s_cselect_b32 s7, s28, s34
	s_add_u32 s30, s30, 0x80080
	s_addc_u32 s31, s31, 0
	s_add_u32 s57, s34, 0x100
	v_mov_b32_e32 v0, 0
	s_addc_u32 s58, s35, 0
	s_mov_b32 s59, -2
	v_mov_b32_e32 v1, v0
	v_mov_b32_e32 v2, v0
	v_mov_b32_e32 v3, v0
	v_mov_b32_e32 v4, v0
	v_mov_b32_e32 v5, v0
	v_mov_b32_e32 v6, v0
	v_mov_b32_e32 v7, v0
	v_mov_b32_e32 v8, v0
	v_mov_b32_e32 v9, v0
	v_mov_b32_e32 v10, v0
	v_mov_b32_e32 v11, v0
	v_mov_b32_e32 v12, v0
	v_mov_b32_e32 v13, v0
	v_mov_b32_e32 v14, v0
	v_mov_b32_e32 v15, v0
	v_mov_b32_e32 v24, v0
	v_mov_b32_e32 v25, v0
	v_mov_b32_e32 v26, v0
	v_mov_b32_e32 v27, v0
	v_mov_b32_e32 v28, v0
	v_mov_b32_e32 v29, v0
	v_mov_b32_e32 v30, v0
	v_mov_b32_e32 v31, v0
	v_mov_b32_e32 v40, v0
	v_mov_b32_e32 v41, v0
	v_mov_b32_e32 v42, v0
	v_mov_b32_e32 v43, v0
	v_mov_b32_e32 v44, v0
	v_mov_b32_e32 v45, v0
	v_mov_b32_e32 v46, v0
	v_mov_b32_e32 v47, v0
	v_mov_b32_e32 v16, v0
	v_mov_b32_e32 v17, v0
	v_mov_b32_e32 v18, v0
	v_mov_b32_e32 v19, v0
	v_mov_b32_e32 v20, v0
	v_mov_b32_e32 v21, v0
	v_mov_b32_e32 v22, v0
	v_mov_b32_e32 v23, v0
	v_mov_b32_e32 v32, v0
	v_mov_b32_e32 v33, v0
	v_mov_b32_e32 v34, v0
	v_mov_b32_e32 v35, v0
	v_mov_b32_e32 v36, v0
	v_mov_b32_e32 v37, v0
	v_mov_b32_e32 v38, v0
	v_mov_b32_e32 v39, v0
	v_mov_b32_e32 v48, v0
	v_mov_b32_e32 v49, v0
	v_mov_b32_e32 v50, v0
	v_mov_b32_e32 v51, v0
	v_mov_b32_e32 v52, v0
	v_mov_b32_e32 v53, v0
	v_mov_b32_e32 v54, v0
	v_mov_b32_e32 v55, v0
	v_mov_b32_e32 v56, v0
	v_mov_b32_e32 v57, v0
	v_mov_b32_e32 v58, v0
	v_mov_b32_e32 v59, v0
	v_mov_b32_e32 v60, v0
	v_mov_b32_e32 v61, v0
	v_mov_b32_e32 v62, v0
	v_mov_b32_e32 v63, v0
	v_mov_b32_e32 v64, v0
	v_mov_b32_e32 v65, v0
	v_mov_b32_e32 v66, v0
	v_mov_b32_e32 v67, v0
	v_mov_b32_e32 v68, v0
	v_mov_b32_e32 v69, v0
	v_mov_b32_e32 v70, v0
	v_mov_b32_e32 v71, v0
	v_mov_b32_e32 v72, v0
	v_mov_b32_e32 v73, v0
	v_mov_b32_e32 v74, v0
	v_mov_b32_e32 v75, v0
	v_mov_b32_e32 v76, v0
	v_mov_b32_e32 v77, v0
	v_mov_b32_e32 v78, v0
	v_mov_b32_e32 v79, v0
	v_mov_b32_e32 v88, v0
	v_mov_b32_e32 v89, v0
	v_mov_b32_e32 v90, v0
	v_mov_b32_e32 v91, v0
	v_mov_b32_e32 v92, v0
	v_mov_b32_e32 v93, v0
	v_mov_b32_e32 v94, v0
	v_mov_b32_e32 v95, v0
	v_mov_b32_e32 v104, v0
	v_mov_b32_e32 v105, v0
	v_mov_b32_e32 v106, v0
	v_mov_b32_e32 v107, v0
	v_mov_b32_e32 v108, v0
	v_mov_b32_e32 v109, v0
	v_mov_b32_e32 v110, v0
	v_mov_b32_e32 v111, v0
	v_mov_b32_e32 v80, v0
	v_mov_b32_e32 v81, v0
	v_mov_b32_e32 v82, v0
	v_mov_b32_e32 v83, v0
	v_mov_b32_e32 v84, v0
	v_mov_b32_e32 v85, v0
	v_mov_b32_e32 v86, v0
	v_mov_b32_e32 v87, v0
	v_mov_b32_e32 v96, v0
	v_mov_b32_e32 v97, v0
	v_mov_b32_e32 v98, v0
	v_mov_b32_e32 v99, v0
	v_mov_b32_e32 v100, v0
	v_mov_b32_e32 v101, v0
	v_mov_b32_e32 v102, v0
	v_mov_b32_e32 v103, v0
	v_mov_b32_e32 v112, v0
	v_mov_b32_e32 v113, v0
	v_mov_b32_e32 v114, v0
	v_mov_b32_e32 v115, v0
	v_mov_b32_e32 v116, v0
	v_mov_b32_e32 v117, v0
	v_mov_b32_e32 v118, v0
	v_mov_b32_e32 v119, v0
	v_mov_b32_e32 v120, v0
	v_mov_b32_e32 v121, v0
	v_mov_b32_e32 v122, v0
	v_mov_b32_e32 v123, v0
	v_mov_b32_e32 v124, v0
	v_mov_b32_e32 v125, v0
	v_mov_b32_e32 v126, v0
	v_mov_b32_e32 v127, v0
	.p2align	6

; template <class Epi, class Sched, bool ALIGN_EPI = true, bool SP2 = true>
; __device__ __forceinline__ void gemm_phase(LAS unsigned char* lds, const bf16_t* Ag, const bf16_t* Btg, const int K, const int lda, const int ldb, const Sched& S, const Epi& E) {
;     ...
;         const bool has_next = S.next(ui + 1, nxt);
;         const char* nA = has_next ? (const char*)Ag + nxt.aoff : cA; const char* nB = has_next ? (const char*)Btg + nxt.boff : cB;
;     ...
; #pragma unroll
;         for (int a = 0; a < 2; ++a)
; #pragma unroll
;             for (int b = 0; b < 2; ++b)
; #pragma unroll
;                 for (int m = 0; m < 4; ++m)
; #pragma unroll
;                     for (int n = 0; n < 2; ++n) acc[a][b][m][n] = (f32x4){0.f, 0.f, 0.f, 0.f};
;         cur = nxt; cA = nA; cB = nB; ++ui;
.LBB0_301:
	s_add_u32 s24, s37, s16
	s_addc_u32 s25, s40, s17
	s_and_b64 s[26:27], s[14:15], exec
	s_cselect_b32 s56, s25, s29
	s_cselect_b32 s57, s24, s28
	s_add_u32 s26, s33, s18
	s_addc_u32 s27, s38, s19
	s_and_b64 s[34:35], s[14:15], exec
	s_cselect_b32 s58, s27, s31
	s_cselect_b32 s59, s26, s30
	s_add_u32 s28, s28, 0x80080
	s_addc_u32 s29, s29, 0
	s_add_u32 s60, s30, 0x100
	v_mov_b32_e32 v0, 0
	s_addc_u32 s61, s31, 0
	s_mov_b32 s62, -2
	v_mov_b32_e32 v1, v0
	v_mov_b32_e32 v2, v0
	v_mov_b32_e32 v3, v0
	v_mov_b32_e32 v4, v0
	v_mov_b32_e32 v5, v0
	v_mov_b32_e32 v6, v0
	v_mov_b32_e32 v7, v0
	v_mov_b32_e32 v8, v0
	v_mov_b32_e32 v9, v0
	v_mov_b32_e32 v10, v0
	v_mov_b32_e32 v11, v0
	v_mov_b32_e32 v12, v0
	v_mov_b32_e32 v13, v0
	v_mov_b32_e32 v14, v0
	v_mov_b32_e32 v15, v0
	v_mov_b32_e32 v24, v0
	v_mov_b32_e32 v25, v0
	v_mov_b32_e32 v26, v0
	v_mov_b32_e32 v27, v0
	v_mov_b32_e32 v28, v0
	v_mov_b32_e32 v29, v0
	v_mov_b32_e32 v30, v0
	v_mov_b32_e32 v31, v0
	v_mov_b32_e32 v40, v0
	v_mov_b32_e32 v41, v0
	v_mov_b32_e32 v42, v0
	v_mov_b32_e32 v43, v0
	v_mov_b32_e32 v44, v0
	v_mov_b32_e32 v45, v0
	v_mov_b32_e32 v46, v0
	v_mov_b32_e32 v47, v0
	v_mov_b32_e32 v16, v0
	v_mov_b32_e32 v17, v0
	v_mov_b32_e32 v18, v0
	v_mov_b32_e32 v19, v0
	v_mov_b32_e32 v20, v0
	v_mov_b32_e32 v21, v0
	v_mov_b32_e32 v22, v0
	v_mov_b32_e32 v23, v0
	v_mov_b32_e32 v32, v0
	v_mov_b32_e32 v33, v0
	v_mov_b32_e32 v34, v0
	v_mov_b32_e32 v35, v0
	v_mov_b32_e32 v36, v0
	v_mov_b32_e32 v37, v0
	v_mov_b32_e32 v38, v0
	v_mov_b32_e32 v39, v0
	v_mov_b32_e32 v48, v0
	v_mov_b32_e32 v49, v0
	v_mov_b32_e32 v50, v0
	v_mov_b32_e32 v51, v0
	v_mov_b32_e32 v52, v0
	v_mov_b32_e32 v53, v0
	v_mov_b32_e32 v54, v0
	v_mov_b32_e32 v55, v0
	v_mov_b32_e32 v56, v0
	v_mov_b32_e32 v57, v0
	v_mov_b32_e32 v58, v0
	v_mov_b32_e32 v59, v0
	v_mov_b32_e32 v60, v0
	v_mov_b32_e32 v61, v0
	v_mov_b32_e32 v62, v0
	v_mov_b32_e32 v63, v0
	v_mov_b32_e32 v64, v0
	v_mov_b32_e32 v65, v0
	v_mov_b32_e32 v66, v0
	v_mov_b32_e32 v67, v0
	v_mov_b32_e32 v68, v0
	v_mov_b32_e32 v69, v0
	v_mov_b32_e32 v70, v0
	v_mov_b32_e32 v71, v0
	v_mov_b32_e32 v72, v0
	v_mov_b32_e32 v73, v0
	v_mov_b32_e32 v74, v0
	v_mov_b32_e32 v75, v0
	v_mov_b32_e32 v76, v0
	v_mov_b32_e32 v77, v0
	v_mov_b32_e32 v78, v0
	v_mov_b32_e32 v79, v0
	v_mov_b32_e32 v88, v0
	v_mov_b32_e32 v89, v0
	v_mov_b32_e32 v90, v0
	v_mov_b32_e32 v91, v0
	v_mov_b32_e32 v92, v0
	v_mov_b32_e32 v93, v0
	v_mov_b32_e32 v94, v0
	v_mov_b32_e32 v95, v0
	v_mov_b32_e32 v104, v0
	v_mov_b32_e32 v105, v0
	v_mov_b32_e32 v106, v0
	v_mov_b32_e32 v107, v0
	v_mov_b32_e32 v108, v0
	v_mov_b32_e32 v109, v0
	v_mov_b32_e32 v110, v0
	v_mov_b32_e32 v111, v0
	v_mov_b32_e32 v80, v0
	v_mov_b32_e32 v81, v0
	v_mov_b32_e32 v82, v0
	v_mov_b32_e32 v83, v0
	v_mov_b32_e32 v84, v0
	v_mov_b32_e32 v85, v0
	v_mov_b32_e32 v86, v0
	v_mov_b32_e32 v87, v0
	v_mov_b32_e32 v96, v0
	v_mov_b32_e32 v97, v0
	v_mov_b32_e32 v98, v0
	v_mov_b32_e32 v99, v0
	v_mov_b32_e32 v100, v0
	v_mov_b32_e32 v101, v0
	v_mov_b32_e32 v102, v0
	v_mov_b32_e32 v103, v0
	v_mov_b32_e32 v112, v0
	v_mov_b32_e32 v113, v0
	v_mov_b32_e32 v114, v0
	v_mov_b32_e32 v115, v0
	v_mov_b32_e32 v116, v0
	v_mov_b32_e32 v117, v0
	v_mov_b32_e32 v118, v0
	v_mov_b32_e32 v119, v0
	v_mov_b32_e32 v120, v0
	v_mov_b32_e32 v121, v0
	v_mov_b32_e32 v122, v0
	v_mov_b32_e32 v123, v0
	v_mov_b32_e32 v124, v0
	v_mov_b32_e32 v125, v0
	v_mov_b32_e32 v126, v0
	v_mov_b32_e32 v127, v0
	.p2align	6

; template <class Epi, class Sched, bool ALIGN_EPI = true, bool SP2 = true>
; __device__ __forceinline__ void gemm_phase(LAS unsigned char* lds, const bf16_t* Ag, const bf16_t* Btg, const int K, const int lda, const int ldb, const Sched& S, const Epi& E) {
;     ...
;         const bool has_next = S.next(ui + 1, nxt);
;         const char* nA = has_next ? (const char*)Ag + nxt.aoff : cA; const char* nB = has_next ? (const char*)Btg + nxt.boff : cB;
;     ...
; #pragma unroll
;         for (int a = 0; a < 2; ++a)
; #pragma unroll
;             for (int b = 0; b < 2; ++b)
; #pragma unroll
;                 for (int m = 0; m < 4; ++m)
; #pragma unroll
;                     for (int n = 0; n < 2; ++n) acc[a][b][m][n] = (f32x4){0.f, 0.f, 0.f, 0.f};
;         cur = nxt; cA = nA; cB = nB; ++ui;
.LBB0_386:
	s_add_u32 s28, s80, s24
	s_addc_u32 s29, s81, s25
	s_and_b64 s[30:31], s[2:3], exec
	s_cselect_b32 s1, s29, s5
	s_cselect_b32 s9, s28, s4
	s_add_u32 s30, s78, s26
	s_addc_u32 s31, s79, s27
	s_and_b64 s[34:35], s[2:3], exec
	s_cselect_b32 s15, s31, s7
	s_cselect_b32 s21, s30, s6
	s_add_u32 s4, s4, 0x80080
	s_addc_u32 s5, s5, 0
	s_add_u32 s23, s6, 0x100
	v_mov_b32_e32 v0, 0
	s_addc_u32 s33, s7, 0
	s_mov_b32 s38, -2
	v_mov_b32_e32 v1, v0
	v_mov_b32_e32 v2, v0
	v_mov_b32_e32 v3, v0
	v_mov_b32_e32 v4, v0
	v_mov_b32_e32 v5, v0
	v_mov_b32_e32 v6, v0
	v_mov_b32_e32 v7, v0
	v_mov_b32_e32 v8, v0
	v_mov_b32_e32 v9, v0
	v_mov_b32_e32 v10, v0
	v_mov_b32_e32 v11, v0
	v_mov_b32_e32 v12, v0
	v_mov_b32_e32 v13, v0
	v_mov_b32_e32 v14, v0
	v_mov_b32_e32 v15, v0
	v_mov_b32_e32 v16, v0
	v_mov_b32_e32 v17, v0
	v_mov_b32_e32 v18, v0
	v_mov_b32_e32 v19, v0
	v_mov_b32_e32 v20, v0
	v_mov_b32_e32 v21, v0
	v_mov_b32_e32 v22, v0
	v_mov_b32_e32 v23, v0
	v_mov_b32_e32 v24, v0
	v_mov_b32_e32 v25, v0
	v_mov_b32_e32 v26, v0
	v_mov_b32_e32 v27, v0
	v_mov_b32_e32 v28, v0
	v_mov_b32_e32 v29, v0
	v_mov_b32_e32 v30, v0
	v_mov_b32_e32 v31, v0
	v_mov_b32_e32 v64, v0
	v_mov_b32_e32 v65, v0
	v_mov_b32_e32 v66, v0
	v_mov_b32_e32 v67, v0
	v_mov_b32_e32 v68, v0
	v_mov_b32_e32 v69, v0
	v_mov_b32_e32 v70, v0
	v_mov_b32_e32 v71, v0
	v_mov_b32_e32 v72, v0
	v_mov_b32_e32 v73, v0
	v_mov_b32_e32 v74, v0
	v_mov_b32_e32 v75, v0
	v_mov_b32_e32 v76, v0
	v_mov_b32_e32 v77, v0
	v_mov_b32_e32 v78, v0
	v_mov_b32_e32 v79, v0
	v_mov_b32_e32 v88, v0
	v_mov_b32_e32 v89, v0
	v_mov_b32_e32 v90, v0
	v_mov_b32_e32 v91, v0
	v_mov_b32_e32 v92, v0
	v_mov_b32_e32 v93, v0
	v_mov_b32_e32 v94, v0
	v_mov_b32_e32 v95, v0
	v_mov_b32_e32 v96, v0
	v_mov_b32_e32 v97, v0
	v_mov_b32_e32 v98, v0
	v_mov_b32_e32 v99, v0
	v_mov_b32_e32 v100, v0
	v_mov_b32_e32 v101, v0
	v_mov_b32_e32 v102, v0
	v_mov_b32_e32 v103, v0
	v_mov_b32_e32 v32, v0
	v_mov_b32_e32 v33, v0
	v_mov_b32_e32 v34, v0
	v_mov_b32_e32 v35, v0
	v_mov_b32_e32 v36, v0
	v_mov_b32_e32 v37, v0
	v_mov_b32_e32 v38, v0
	v_mov_b32_e32 v39, v0
	v_mov_b32_e32 v40, v0
	v_mov_b32_e32 v41, v0
	v_mov_b32_e32 v42, v0
	v_mov_b32_e32 v43, v0
	v_mov_b32_e32 v44, v0
	v_mov_b32_e32 v45, v0
	v_mov_b32_e32 v46, v0
	v_mov_b32_e32 v47, v0
	v_mov_b32_e32 v48, v0
	v_mov_b32_e32 v49, v0
	v_mov_b32_e32 v50, v0
	v_mov_b32_e32 v51, v0
	v_mov_b32_e32 v52, v0
	v_mov_b32_e32 v53, v0
	v_mov_b32_e32 v54, v0
	v_mov_b32_e32 v55, v0
	v_mov_b32_e32 v56, v0
	v_mov_b32_e32 v57, v0
	v_mov_b32_e32 v58, v0
	v_mov_b32_e32 v59, v0
	v_mov_b32_e32 v60, v0
	v_mov_b32_e32 v61, v0
	v_mov_b32_e32 v62, v0
	v_mov_b32_e32 v63, v0
	v_mov_b32_e32 v104, v0
	v_mov_b32_e32 v105, v0
	v_mov_b32_e32 v106, v0
	v_mov_b32_e32 v107, v0
	v_mov_b32_e32 v108, v0
	v_mov_b32_e32 v109, v0
	v_mov_b32_e32 v110, v0
	v_mov_b32_e32 v111, v0
	v_mov_b32_e32 v112, v0
	v_mov_b32_e32 v113, v0
	v_mov_b32_e32 v114, v0
	v_mov_b32_e32 v115, v0
	v_mov_b32_e32 v116, v0
	v_mov_b32_e32 v117, v0
	v_mov_b32_e32 v118, v0
	v_mov_b32_e32 v119, v0
	v_mov_b32_e32 v120, v0
	v_mov_b32_e32 v121, v0
	v_mov_b32_e32 v122, v0
	v_mov_b32_e32 v123, v0
	v_mov_b32_e32 v124, v0
	v_mov_b32_e32 v125, v0
	v_mov_b32_e32 v126, v0
	v_mov_b32_e32 v127, v0
	v_mov_b32_e32 v128, v0
	v_mov_b32_e32 v129, v0
	v_mov_b32_e32 v130, v0
	v_mov_b32_e32 v131, v0
	v_mov_b32_e32 v132, v0
	v_mov_b32_e32 v133, v0
	v_mov_b32_e32 v134, v0
	v_mov_b32_e32 v135, v0
	.p2align	6

; template <class Epi, class Sched, bool ALIGN_EPI = true, bool SP2 = true>
; __device__ __forceinline__ void gemm_phase(LAS unsigned char* lds, const bf16_t* Ag, const bf16_t* Btg, const int K, const int lda, const int ldb, const Sched& S, const Epi& E) {
;     ...
;         const bool has_next = S.next(ui + 1, nxt);
;         const char* nA = has_next ? (const char*)Ag + nxt.aoff : cA; const char* nB = has_next ? (const char*)Btg + nxt.boff : cB;
;     ...
; #pragma unroll
;         for (int a = 0; a < 2; ++a)
; #pragma unroll
;             for (int b = 0; b < 2; ++b)
; #pragma unroll
;                 for (int m = 0; m < 4; ++m)
; #pragma unroll
;                     for (int n = 0; n < 2; ++n) acc[a][b][m][n] = (f32x4){0.f, 0.f, 0.f, 0.f};
;         cur = nxt; cA = nA; cB = nB; ++ui;
.LBB0_786:
	s_add_u32 s18, s80, s14
	s_addc_u32 s19, s81, s15
	s_and_b64 s[20:21], s[2:3], exec
	s_cselect_b32 s11, s19, s25
	s_cselect_b32 s13, s18, s24
	s_add_u32 s20, s31, s16
	s_addc_u32 s21, s34, s17
	s_and_b64 s[28:29], s[2:3], exec
	s_cselect_b32 s33, s21, s27
	s_cselect_b32 s50, s20, s26
	s_add_u32 s24, s24, 0x80080
	s_addc_u32 s25, s25, 0
	s_add_u32 s51, s26, 0x100
	v_mov_b32_e32 v0, 0
	s_addc_u32 s52, s27, 0
	s_mov_b32 s53, -2
	v_mov_b32_e32 v1, v0
	v_mov_b32_e32 v2, v0
	v_mov_b32_e32 v3, v0
	v_mov_b32_e32 v4, v0
	v_mov_b32_e32 v5, v0
	v_mov_b32_e32 v6, v0
	v_mov_b32_e32 v7, v0
	v_mov_b32_e32 v8, v0
	v_mov_b32_e32 v9, v0
	v_mov_b32_e32 v10, v0
	v_mov_b32_e32 v11, v0
	v_mov_b32_e32 v12, v0
	v_mov_b32_e32 v13, v0
	v_mov_b32_e32 v14, v0
	v_mov_b32_e32 v15, v0
	v_mov_b32_e32 v16, v0
	v_mov_b32_e32 v17, v0
	v_mov_b32_e32 v18, v0
	v_mov_b32_e32 v19, v0
	v_mov_b32_e32 v20, v0
	v_mov_b32_e32 v21, v0
	v_mov_b32_e32 v22, v0
	v_mov_b32_e32 v23, v0
	v_mov_b32_e32 v24, v0
	v_mov_b32_e32 v25, v0
	v_mov_b32_e32 v26, v0
	v_mov_b32_e32 v27, v0
	v_mov_b32_e32 v28, v0
	v_mov_b32_e32 v29, v0
	v_mov_b32_e32 v30, v0
	v_mov_b32_e32 v31, v0
	v_mov_b32_e32 v64, v0
	v_mov_b32_e32 v65, v0
	v_mov_b32_e32 v66, v0
	v_mov_b32_e32 v67, v0
	v_mov_b32_e32 v68, v0
	v_mov_b32_e32 v69, v0
	v_mov_b32_e32 v70, v0
	v_mov_b32_e32 v71, v0
	v_mov_b32_e32 v72, v0
	v_mov_b32_e32 v73, v0
	v_mov_b32_e32 v74, v0
	v_mov_b32_e32 v75, v0
	v_mov_b32_e32 v76, v0
	v_mov_b32_e32 v77, v0
	v_mov_b32_e32 v78, v0
	v_mov_b32_e32 v79, v0
	v_mov_b32_e32 v80, v0
	v_mov_b32_e32 v81, v0
	v_mov_b32_e32 v82, v0
	v_mov_b32_e32 v83, v0
	v_mov_b32_e32 v84, v0
	v_mov_b32_e32 v85, v0
	v_mov_b32_e32 v86, v0
	v_mov_b32_e32 v87, v0
	v_mov_b32_e32 v88, v0
	v_mov_b32_e32 v89, v0
	v_mov_b32_e32 v90, v0
	v_mov_b32_e32 v91, v0
	v_mov_b32_e32 v92, v0
	v_mov_b32_e32 v93, v0
	v_mov_b32_e32 v94, v0
	v_mov_b32_e32 v95, v0
	v_mov_b32_e32 v32, v0
	v_mov_b32_e32 v33, v0
	v_mov_b32_e32 v34, v0
	v_mov_b32_e32 v35, v0
	v_mov_b32_e32 v36, v0
	v_mov_b32_e32 v37, v0
	v_mov_b32_e32 v38, v0
	v_mov_b32_e32 v39, v0
	v_mov_b32_e32 v40, v0
	v_mov_b32_e32 v41, v0
	v_mov_b32_e32 v42, v0
	v_mov_b32_e32 v43, v0
	v_mov_b32_e32 v44, v0
	v_mov_b32_e32 v45, v0
	v_mov_b32_e32 v46, v0
	v_mov_b32_e32 v47, v0
	v_mov_b32_e32 v48, v0
	v_mov_b32_e32 v49, v0
	v_mov_b32_e32 v50, v0
	v_mov_b32_e32 v51, v0
	v_mov_b32_e32 v52, v0
	v_mov_b32_e32 v53, v0
	v_mov_b32_e32 v54, v0
	v_mov_b32_e32 v55, v0
	v_mov_b32_e32 v56, v0
	v_mov_b32_e32 v57, v0
	v_mov_b32_e32 v58, v0
	v_mov_b32_e32 v59, v0
	v_mov_b32_e32 v60, v0
	v_mov_b32_e32 v61, v0
	v_mov_b32_e32 v62, v0
	v_mov_b32_e32 v63, v0
	v_mov_b32_e32 v96, v0
	v_mov_b32_e32 v97, v0
	v_mov_b32_e32 v98, v0
	v_mov_b32_e32 v99, v0
	v_mov_b32_e32 v100, v0
	v_mov_b32_e32 v101, v0
	v_mov_b32_e32 v102, v0
	v_mov_b32_e32 v103, v0
	v_mov_b32_e32 v104, v0
	v_mov_b32_e32 v105, v0
	v_mov_b32_e32 v106, v0
	v_mov_b32_e32 v107, v0
	v_mov_b32_e32 v116, v0
	v_mov_b32_e32 v117, v0
	v_mov_b32_e32 v118, v0
	v_mov_b32_e32 v119, v0
	v_mov_b32_e32 v120, v0
	v_mov_b32_e32 v121, v0
	v_mov_b32_e32 v122, v0
	v_mov_b32_e32 v123, v0
	v_mov_b32_e32 v124, v0
	v_mov_b32_e32 v125, v0
	v_mov_b32_e32 v126, v0
	v_mov_b32_e32 v127, v0
	v_mov_b32_e32 v128, v0
	v_mov_b32_e32 v129, v0
	v_mov_b32_e32 v130, v0
	v_mov_b32_e32 v131, v0
	v_mov_b32_e32 v132, v0
	v_mov_b32_e32 v133, v0
	v_mov_b32_e32 v134, v0
	v_mov_b32_e32 v135, v0
	.p2align	6

; template <class Epi, class Sched, bool ALIGN_EPI = true, bool SP2 = true>
; __device__ __forceinline__ void gemm_phase(LAS unsigned char* lds, const bf16_t* Ag, const bf16_t* Btg, const int K, const int lda, const int ldb, const Sched& S, const Epi& E) {
;     ...
;         const bool has_next = S.next(ui + 1, nxt);
;         const char* nA = has_next ? (const char*)Ag + nxt.aoff : cA; const char* nB = has_next ? (const char*)Btg + nxt.boff : cB;
;     ...
; #pragma unroll
;         for (int a = 0; a < 2; ++a)
; #pragma unroll
;             for (int b = 0; b < 2; ++b)
; #pragma unroll
;                 for (int m = 0; m < 4; ++m)
; #pragma unroll
;                     for (int n = 0; n < 2; ++n) acc[a][b][m][n] = (f32x4){0.f, 0.f, 0.f, 0.f};
;         cur = nxt; cA = nA; cB = nB; ++ui;
.LBB0_865:
	s_add_u32 s20, s62, s16
	s_addc_u32 s21, s63, s17
	s_and_b64 s[22:23], s[2:3], exec
	v_readlane_b32 s22, v245, 41
	s_cselect_b32 s13, s21, s27
	s_cselect_b32 s15, s20, s26
	v_readlane_b32 s23, v245, 42
	s_add_u32 s22, s22, s18
	s_addc_u32 s23, s23, s19
	s_and_b64 s[30:31], s[2:3], exec
	s_cselect_b32 s47, s23, s29
	s_cselect_b32 s50, s22, s28
	s_add_u32 s26, s26, 0x80080
	s_addc_u32 s27, s27, 0
	s_add_u32 s51, s28, 0x100
	v_mov_b32_e32 v0, 0
	s_addc_u32 s52, s29, 0
	s_mov_b32 s53, -2
	v_mov_b32_e32 v1, v0
	v_mov_b32_e32 v2, v0
	v_mov_b32_e32 v3, v0
	v_mov_b32_e32 v4, v0
	v_mov_b32_e32 v5, v0
	v_mov_b32_e32 v6, v0
	v_mov_b32_e32 v7, v0
	v_mov_b32_e32 v16, v0
	v_mov_b32_e32 v17, v0
	v_mov_b32_e32 v18, v0
	v_mov_b32_e32 v19, v0
	v_mov_b32_e32 v20, v0
	v_mov_b32_e32 v21, v0
	v_mov_b32_e32 v22, v0
	v_mov_b32_e32 v23, v0
	v_mov_b32_e32 v32, v0
	v_mov_b32_e32 v33, v0
	v_mov_b32_e32 v34, v0
	v_mov_b32_e32 v35, v0
	v_mov_b32_e32 v36, v0
	v_mov_b32_e32 v37, v0
	v_mov_b32_e32 v38, v0
	v_mov_b32_e32 v39, v0
	v_mov_b32_e32 v48, v0
	v_mov_b32_e32 v49, v0
	v_mov_b32_e32 v50, v0
	v_mov_b32_e32 v51, v0
	v_mov_b32_e32 v52, v0
	v_mov_b32_e32 v53, v0
	v_mov_b32_e32 v54, v0
	v_mov_b32_e32 v55, v0
	v_mov_b32_e32 v8, v0
	v_mov_b32_e32 v9, v0
	v_mov_b32_e32 v10, v0
	v_mov_b32_e32 v11, v0
	v_mov_b32_e32 v12, v0
	v_mov_b32_e32 v13, v0
	v_mov_b32_e32 v14, v0
	v_mov_b32_e32 v15, v0
	v_mov_b32_e32 v24, v0
	v_mov_b32_e32 v25, v0
	v_mov_b32_e32 v26, v0
	v_mov_b32_e32 v27, v0
	v_mov_b32_e32 v28, v0
	v_mov_b32_e32 v29, v0
	v_mov_b32_e32 v30, v0
	v_mov_b32_e32 v31, v0
	v_mov_b32_e32 v40, v0
	v_mov_b32_e32 v41, v0
	v_mov_b32_e32 v42, v0
	v_mov_b32_e32 v43, v0
	v_mov_b32_e32 v44, v0
	v_mov_b32_e32 v45, v0
	v_mov_b32_e32 v46, v0
	v_mov_b32_e32 v47, v0
	v_mov_b32_e32 v56, v0
	v_mov_b32_e32 v57, v0
	v_mov_b32_e32 v58, v0
	v_mov_b32_e32 v59, v0
	v_mov_b32_e32 v60, v0
	v_mov_b32_e32 v61, v0
	v_mov_b32_e32 v62, v0
	v_mov_b32_e32 v63, v0
	v_mov_b32_e32 v64, v0
	v_mov_b32_e32 v65, v0
	v_mov_b32_e32 v66, v0
	v_mov_b32_e32 v67, v0
	v_mov_b32_e32 v68, v0
	v_mov_b32_e32 v69, v0
	v_mov_b32_e32 v70, v0
	v_mov_b32_e32 v71, v0
	v_mov_b32_e32 v80, v0
	v_mov_b32_e32 v81, v0
	v_mov_b32_e32 v82, v0
	v_mov_b32_e32 v83, v0
	v_mov_b32_e32 v84, v0
	v_mov_b32_e32 v85, v0
	v_mov_b32_e32 v86, v0
	v_mov_b32_e32 v87, v0
	v_mov_b32_e32 v96, v0
	v_mov_b32_e32 v97, v0
	v_mov_b32_e32 v98, v0
	v_mov_b32_e32 v99, v0
	v_mov_b32_e32 v100, v0
	v_mov_b32_e32 v101, v0
	v_mov_b32_e32 v102, v0
	v_mov_b32_e32 v103, v0
	v_mov_b32_e32 v112, v0
	v_mov_b32_e32 v113, v0
	v_mov_b32_e32 v114, v0
	v_mov_b32_e32 v115, v0
	v_mov_b32_e32 v116, v0
	v_mov_b32_e32 v117, v0
	v_mov_b32_e32 v118, v0
	v_mov_b32_e32 v119, v0
	v_mov_b32_e32 v72, v0
	v_mov_b32_e32 v73, v0
	v_mov_b32_e32 v74, v0
	v_mov_b32_e32 v75, v0
	v_mov_b32_e32 v76, v0
	v_mov_b32_e32 v77, v0
	v_mov_b32_e32 v78, v0
	v_mov_b32_e32 v79, v0
	v_mov_b32_e32 v88, v0
	v_mov_b32_e32 v89, v0
	v_mov_b32_e32 v90, v0
	v_mov_b32_e32 v91, v0
	v_mov_b32_e32 v92, v0
	v_mov_b32_e32 v93, v0
	v_mov_b32_e32 v94, v0
	v_mov_b32_e32 v95, v0
	v_mov_b32_e32 v104, v0
	v_mov_b32_e32 v105, v0
	v_mov_b32_e32 v106, v0
	v_mov_b32_e32 v107, v0
	v_mov_b32_e32 v108, v0
	v_mov_b32_e32 v109, v0
	v_mov_b32_e32 v110, v0
	v_mov_b32_e32 v111, v0
	v_mov_b32_e32 v120, v0
	v_mov_b32_e32 v121, v0
	v_mov_b32_e32 v122, v0
	v_mov_b32_e32 v123, v0
	v_mov_b32_e32 v124, v0
	v_mov_b32_e32 v125, v0
	v_mov_b32_e32 v126, v0
	v_mov_b32_e32 v127, v0
	.p2align	6

; template <class Epi, class Sched, bool ALIGN_EPI = true, bool SP2 = true>
; __device__ __forceinline__ void gemm_phase(LAS unsigned char* lds, const bf16_t* Ag, const bf16_t* Btg, const int K, const int lda, const int ldb, const Sched& S, const Epi& E) {
;     ...
;         const bool has_next = S.next(ui + 1, nxt);
;         const char* nA = has_next ? (const char*)Ag + nxt.aoff : cA; const char* nB = has_next ? (const char*)Btg + nxt.boff : cB;
;     ...
; #pragma unroll
;         for (int a = 0; a < 2; ++a)
; #pragma unroll
;             for (int b = 0; b < 2; ++b)
; #pragma unroll
;                 for (int m = 0; m < 4; ++m)
; #pragma unroll
;                     for (int n = 0; n < 2; ++n) acc[a][b][m][n] = (f32x4){0.f, 0.f, 0.f, 0.f};
;         cur = nxt; cA = nA; cB = nB; ++ui;
.LBB0_889:
	s_add_u32 s20, s35, s16
	s_addc_u32 s21, s37, s17
	s_and_b64 s[22:23], s[2:3], exec
	s_cselect_b32 s13, s21, s27
	s_cselect_b32 s15, s20, s26
	s_add_u32 s22, s38, s18
	s_addc_u32 s23, s39, s19
	s_and_b64 s[30:31], s[2:3], exec
	s_cselect_b32 s33, s23, s29
	s_cselect_b32 s54, s22, s28
	s_add_u32 s26, s26, 0x80080
	s_addc_u32 s27, s27, 0
	s_add_u32 s55, s28, 0x100
	v_mov_b32_e32 v0, 0
	s_addc_u32 s58, s29, 0
	s_mov_b32 s59, -2
	v_mov_b32_e32 v1, v0
	v_mov_b32_e32 v2, v0
	v_mov_b32_e32 v3, v0
	v_mov_b32_e32 v4, v0
	v_mov_b32_e32 v5, v0
	v_mov_b32_e32 v6, v0
	v_mov_b32_e32 v7, v0
	v_mov_b32_e32 v16, v0
	v_mov_b32_e32 v17, v0
	v_mov_b32_e32 v18, v0
	v_mov_b32_e32 v19, v0
	v_mov_b32_e32 v20, v0
	v_mov_b32_e32 v21, v0
	v_mov_b32_e32 v22, v0
	v_mov_b32_e32 v23, v0
	v_mov_b32_e32 v32, v0
	v_mov_b32_e32 v33, v0
	v_mov_b32_e32 v34, v0
	v_mov_b32_e32 v35, v0
	v_mov_b32_e32 v36, v0
	v_mov_b32_e32 v37, v0
	v_mov_b32_e32 v38, v0
	v_mov_b32_e32 v39, v0
	v_mov_b32_e32 v48, v0
	v_mov_b32_e32 v49, v0
	v_mov_b32_e32 v50, v0
	v_mov_b32_e32 v51, v0
	v_mov_b32_e32 v52, v0
	v_mov_b32_e32 v53, v0
	v_mov_b32_e32 v54, v0
	v_mov_b32_e32 v55, v0
	v_mov_b32_e32 v8, v0
	v_mov_b32_e32 v9, v0
	v_mov_b32_e32 v10, v0
	v_mov_b32_e32 v11, v0
	v_mov_b32_e32 v12, v0
	v_mov_b32_e32 v13, v0
	v_mov_b32_e32 v14, v0
	v_mov_b32_e32 v15, v0
	v_mov_b32_e32 v24, v0
	v_mov_b32_e32 v25, v0
	v_mov_b32_e32 v26, v0
	v_mov_b32_e32 v27, v0
	v_mov_b32_e32 v28, v0
	v_mov_b32_e32 v29, v0
	v_mov_b32_e32 v30, v0
	v_mov_b32_e32 v31, v0
	v_mov_b32_e32 v40, v0
	v_mov_b32_e32 v41, v0
	v_mov_b32_e32 v42, v0
	v_mov_b32_e32 v43, v0
	v_mov_b32_e32 v44, v0
	v_mov_b32_e32 v45, v0
	v_mov_b32_e32 v46, v0
	v_mov_b32_e32 v47, v0
	v_mov_b32_e32 v56, v0
	v_mov_b32_e32 v57, v0
	v_mov_b32_e32 v58, v0
	v_mov_b32_e32 v59, v0
	v_mov_b32_e32 v60, v0
	v_mov_b32_e32 v61, v0
	v_mov_b32_e32 v62, v0
	v_mov_b32_e32 v63, v0
	v_mov_b32_e32 v64, v0
	v_mov_b32_e32 v65, v0
	v_mov_b32_e32 v66, v0
	v_mov_b32_e32 v67, v0
	v_mov_b32_e32 v68, v0
	v_mov_b32_e32 v69, v0
	v_mov_b32_e32 v70, v0
	v_mov_b32_e32 v71, v0
	v_mov_b32_e32 v80, v0
	v_mov_b32_e32 v81, v0
	v_mov_b32_e32 v82, v0
	v_mov_b32_e32 v83, v0
	v_mov_b32_e32 v84, v0
	v_mov_b32_e32 v85, v0
	v_mov_b32_e32 v86, v0
	v_mov_b32_e32 v87, v0
	v_mov_b32_e32 v96, v0
	v_mov_b32_e32 v97, v0
	v_mov_b32_e32 v98, v0
	v_mov_b32_e32 v99, v0
	v_mov_b32_e32 v100, v0
	v_mov_b32_e32 v101, v0
	v_mov_b32_e32 v102, v0
	v_mov_b32_e32 v103, v0
	v_mov_b32_e32 v112, v0
	v_mov_b32_e32 v113, v0
	v_mov_b32_e32 v114, v0
	v_mov_b32_e32 v115, v0
	v_mov_b32_e32 v116, v0
	v_mov_b32_e32 v117, v0
	v_mov_b32_e32 v118, v0
	v_mov_b32_e32 v119, v0
	v_mov_b32_e32 v72, v0
	v_mov_b32_e32 v73, v0
	v_mov_b32_e32 v74, v0
	v_mov_b32_e32 v75, v0
	v_mov_b32_e32 v76, v0
	v_mov_b32_e32 v77, v0
	v_mov_b32_e32 v78, v0
	v_mov_b32_e32 v79, v0
	v_mov_b32_e32 v88, v0
	v_mov_b32_e32 v89, v0
	v_mov_b32_e32 v90, v0
	v_mov_b32_e32 v91, v0
	v_mov_b32_e32 v92, v0
	v_mov_b32_e32 v93, v0
	v_mov_b32_e32 v94, v0
	v_mov_b32_e32 v95, v0
	v_mov_b32_e32 v104, v0
	v_mov_b32_e32 v105, v0
	v_mov_b32_e32 v106, v0
	v_mov_b32_e32 v107, v0
	v_mov_b32_e32 v108, v0
	v_mov_b32_e32 v109, v0
	v_mov_b32_e32 v110, v0
	v_mov_b32_e32 v111, v0
	v_mov_b32_e32 v120, v0
	v_mov_b32_e32 v121, v0
	v_mov_b32_e32 v122, v0
	v_mov_b32_e32 v123, v0
	v_mov_b32_e32 v124, v0
	v_mov_b32_e32 v125, v0
	v_mov_b32_e32 v126, v0
	v_mov_b32_e32 v127, v0
	.p2align	6

; template <class Epi, class Sched, bool ALIGN_EPI = true, bool SP2 = true>
; __device__ __forceinline__ void gemm_phase(LAS unsigned char* lds, const bf16_t* Ag, const bf16_t* Btg, const int K, const int lda, const int ldb, const Sched& S, const Epi& E) {
;     ...
;         const bool has_next = S.next(ui + 1, nxt);
;         const char* nA = has_next ? (const char*)Ag + nxt.aoff : cA; const char* nB = has_next ? (const char*)Btg + nxt.boff : cB;
;     ...
; #pragma unroll
;         for (int a = 0; a < 2; ++a)
; #pragma unroll
;             for (int b = 0; b < 2; ++b)
; #pragma unroll
;                 for (int m = 0; m < 4; ++m)
; #pragma unroll
;                     for (int n = 0; n < 2; ++n) acc[a][b][m][n] = (f32x4){0.f, 0.f, 0.f, 0.f};
;         cur = nxt; cA = nA; cB = nB; ++ui;
.LBB0_968:
	v_readlane_b32 s18, v244, 11
	v_readlane_b32 s19, v244, 12
	s_add_u32 s18, s18, s12
	s_addc_u32 s19, s19, s13
	s_and_b64 s[20:21], s[2:3], exec
	v_readlane_b32 s20, v245, 43
	s_cselect_b32 s33, s19, s25
	s_cselect_b32 s47, s18, s24
	v_readlane_b32 s21, v245, 44
	s_add_u32 s20, s20, s14
	s_addc_u32 s21, s21, s15
	s_and_b64 s[28:29], s[2:3], exec
	s_cselect_b32 s50, s21, s27
	s_cselect_b32 s51, s20, s26
	s_add_u32 s24, s24, 0x80080
	s_addc_u32 s25, s25, 0
	s_add_u32 s52, s26, 0x100
	v_mov_b32_e32 v0, 0
	s_addc_u32 s53, s27, 0
	s_mov_b32 s54, -2
	v_mov_b32_e32 v1, v0
	v_mov_b32_e32 v2, v0
	v_mov_b32_e32 v3, v0
	v_mov_b32_e32 v4, v0
	v_mov_b32_e32 v5, v0
	v_mov_b32_e32 v6, v0
	v_mov_b32_e32 v7, v0
	v_mov_b32_e32 v16, v0
	v_mov_b32_e32 v17, v0
	v_mov_b32_e32 v18, v0
	v_mov_b32_e32 v19, v0
	v_mov_b32_e32 v20, v0
	v_mov_b32_e32 v21, v0
	v_mov_b32_e32 v22, v0
	v_mov_b32_e32 v23, v0
	v_mov_b32_e32 v32, v0
	v_mov_b32_e32 v33, v0
	v_mov_b32_e32 v34, v0
	v_mov_b32_e32 v35, v0
	v_mov_b32_e32 v36, v0
	v_mov_b32_e32 v37, v0
	v_mov_b32_e32 v38, v0
	v_mov_b32_e32 v39, v0
	v_mov_b32_e32 v48, v0
	v_mov_b32_e32 v49, v0
	v_mov_b32_e32 v50, v0
	v_mov_b32_e32 v51, v0
	v_mov_b32_e32 v52, v0
	v_mov_b32_e32 v53, v0
	v_mov_b32_e32 v54, v0
	v_mov_b32_e32 v55, v0
	v_mov_b32_e32 v8, v0
	v_mov_b32_e32 v9, v0
	v_mov_b32_e32 v10, v0
	v_mov_b32_e32 v11, v0
	v_mov_b32_e32 v12, v0
	v_mov_b32_e32 v13, v0
	v_mov_b32_e32 v14, v0
	v_mov_b32_e32 v15, v0
	v_mov_b32_e32 v24, v0
	v_mov_b32_e32 v25, v0
	v_mov_b32_e32 v26, v0
	v_mov_b32_e32 v27, v0
	v_mov_b32_e32 v28, v0
	v_mov_b32_e32 v29, v0
	v_mov_b32_e32 v30, v0
	v_mov_b32_e32 v31, v0
	v_mov_b32_e32 v40, v0
	v_mov_b32_e32 v41, v0
	v_mov_b32_e32 v42, v0
	v_mov_b32_e32 v43, v0
	v_mov_b32_e32 v44, v0
	v_mov_b32_e32 v45, v0
	v_mov_b32_e32 v46, v0
	v_mov_b32_e32 v47, v0
	v_mov_b32_e32 v56, v0
	v_mov_b32_e32 v57, v0
	v_mov_b32_e32 v58, v0
	v_mov_b32_e32 v59, v0
	v_mov_b32_e32 v60, v0
	v_mov_b32_e32 v61, v0
	v_mov_b32_e32 v62, v0
	v_mov_b32_e32 v63, v0
	v_mov_b32_e32 v64, v0
	v_mov_b32_e32 v65, v0
	v_mov_b32_e32 v66, v0
	v_mov_b32_e32 v67, v0
	v_mov_b32_e32 v68, v0
	v_mov_b32_e32 v69, v0
	v_mov_b32_e32 v70, v0
	v_mov_b32_e32 v71, v0
	v_mov_b32_e32 v80, v0
	v_mov_b32_e32 v81, v0
	v_mov_b32_e32 v82, v0
	v_mov_b32_e32 v83, v0
	v_mov_b32_e32 v84, v0
	v_mov_b32_e32 v85, v0
	v_mov_b32_e32 v86, v0
	v_mov_b32_e32 v87, v0
	v_mov_b32_e32 v96, v0
	v_mov_b32_e32 v97, v0
	v_mov_b32_e32 v98, v0
	v_mov_b32_e32 v99, v0
	v_mov_b32_e32 v100, v0
	v_mov_b32_e32 v101, v0
	v_mov_b32_e32 v102, v0
	v_mov_b32_e32 v103, v0
	v_mov_b32_e32 v104, v0
	v_mov_b32_e32 v105, v0
	v_mov_b32_e32 v106, v0
	v_mov_b32_e32 v107, v0
	v_mov_b32_e32 v112, v0
	v_mov_b32_e32 v113, v0
	v_mov_b32_e32 v114, v0
	v_mov_b32_e32 v115, v0
	v_mov_b32_e32 v72, v0
	v_mov_b32_e32 v73, v0
	v_mov_b32_e32 v74, v0
	v_mov_b32_e32 v75, v0
	v_mov_b32_e32 v76, v0
	v_mov_b32_e32 v77, v0
	v_mov_b32_e32 v78, v0
	v_mov_b32_e32 v79, v0
	v_mov_b32_e32 v88, v0
	v_mov_b32_e32 v89, v0
	v_mov_b32_e32 v90, v0
	v_mov_b32_e32 v91, v0
	v_mov_b32_e32 v92, v0
	v_mov_b32_e32 v93, v0
	v_mov_b32_e32 v94, v0
	v_mov_b32_e32 v95, v0
	v_mov_b32_e32 v108, v0
	v_mov_b32_e32 v109, v0
	v_mov_b32_e32 v110, v0
	v_mov_b32_e32 v111, v0
	v_mov_b32_e32 v116, v0
	v_mov_b32_e32 v117, v0
	v_mov_b32_e32 v118, v0
	v_mov_b32_e32 v119, v0
	v_mov_b32_e32 v120, v0
	v_mov_b32_e32 v121, v0
	v_mov_b32_e32 v122, v0
	v_mov_b32_e32 v123, v0
	v_mov_b32_e32 v124, v0
	v_mov_b32_e32 v125, v0
	v_mov_b32_e32 v126, v0
	v_mov_b32_e32 v127, v0
	.p2align	6

; template <class Epi, class Sched, bool ALIGN_EPI = true, bool SP2 = true>
; __device__ __forceinline__ void gemm_phase(LAS unsigned char* lds, const bf16_t* Ag, const bf16_t* Btg, const int K, const int lda, const int ldb, const Sched& S, const Epi& E) {
;     ...
;         const bool has_next = S.next(ui + 1, nxt);
;         const char* nA = has_next ? (const char*)Ag + nxt.aoff : cA; const char* nB = has_next ? (const char*)Btg + nxt.boff : cB;
;     ...
; #pragma unroll
;         for (int a = 0; a < 2; ++a)
; #pragma unroll
;             for (int b = 0; b < 2; ++b)
; #pragma unroll
;                 for (int m = 0; m < 4; ++m)
; #pragma unroll
;                     for (int n = 0; n < 2; ++n) acc[a][b][m][n] = (f32x4){0.f, 0.f, 0.f, 0.f};
;         cur = nxt; cA = nA; cB = nB; ++ui;
.LBB0_1037:
	s_add_u32 s16, s68, s10
	s_addc_u32 s17, s69, s11
	s_and_b64 s[18:19], s[26:27], exec
	s_cselect_b32 s53, s17, s23
	s_cselect_b32 s54, s16, s22
	s_add_u32 s18, s30, s52
	s_addc_u32 s19, s31, s1
	s_and_b64 s[26:27], s[26:27], exec
	s_cselect_b32 s55, s19, s25
	s_cselect_b32 s58, s18, s24
	s_add_u32 s22, s22, 0x80080
	s_addc_u32 s23, s23, 0
	s_add_u32 s59, s24, 0x100
	v_mov_b32_e32 v0, 0
	s_addc_u32 s60, s25, 0
	s_mov_b32 s61, -2
	v_mov_b32_e32 v1, v0
	v_mov_b32_e32 v2, v0
	v_mov_b32_e32 v3, v0
	v_mov_b32_e32 v4, v0
	v_mov_b32_e32 v5, v0
	v_mov_b32_e32 v6, v0
	v_mov_b32_e32 v7, v0
	v_mov_b32_e32 v8, v0
	v_mov_b32_e32 v9, v0
	v_mov_b32_e32 v10, v0
	v_mov_b32_e32 v11, v0
	v_mov_b32_e32 v16, v0
	v_mov_b32_e32 v17, v0
	v_mov_b32_e32 v18, v0
	v_mov_b32_e32 v19, v0
	v_mov_b32_e32 v24, v0
	v_mov_b32_e32 v25, v0
	v_mov_b32_e32 v26, v0
	v_mov_b32_e32 v27, v0
	v_mov_b32_e32 v32, v0
	v_mov_b32_e32 v33, v0
	v_mov_b32_e32 v34, v0
	v_mov_b32_e32 v35, v0
	v_mov_b32_e32 v40, v0
	v_mov_b32_e32 v41, v0
	v_mov_b32_e32 v42, v0
	v_mov_b32_e32 v43, v0
	v_mov_b32_e32 v48, v0
	v_mov_b32_e32 v49, v0
	v_mov_b32_e32 v50, v0
	v_mov_b32_e32 v51, v0
	v_mov_b32_e32 v12, v0
	v_mov_b32_e32 v13, v0
	v_mov_b32_e32 v14, v0
	v_mov_b32_e32 v15, v0
	v_mov_b32_e32 v20, v0
	v_mov_b32_e32 v21, v0
	v_mov_b32_e32 v22, v0
	v_mov_b32_e32 v23, v0
	v_mov_b32_e32 v28, v0
	v_mov_b32_e32 v29, v0
	v_mov_b32_e32 v30, v0
	v_mov_b32_e32 v31, v0
	v_mov_b32_e32 v36, v0
	v_mov_b32_e32 v37, v0
	v_mov_b32_e32 v38, v0
	v_mov_b32_e32 v39, v0
	v_mov_b32_e32 v44, v0
	v_mov_b32_e32 v45, v0
	v_mov_b32_e32 v46, v0
	v_mov_b32_e32 v47, v0
	v_mov_b32_e32 v52, v0
	v_mov_b32_e32 v53, v0
	v_mov_b32_e32 v54, v0
	v_mov_b32_e32 v55, v0
	v_mov_b32_e32 v56, v0
	v_mov_b32_e32 v57, v0
	v_mov_b32_e32 v58, v0
	v_mov_b32_e32 v59, v0
	v_mov_b32_e32 v60, v0
	v_mov_b32_e32 v61, v0
	v_mov_b32_e32 v62, v0
	v_mov_b32_e32 v63, v0
	v_mov_b32_e32 v64, v0
	v_mov_b32_e32 v65, v0
	v_mov_b32_e32 v66, v0
	v_mov_b32_e32 v67, v0
	v_mov_b32_e32 v68, v0
	v_mov_b32_e32 v69, v0
	v_mov_b32_e32 v70, v0
	v_mov_b32_e32 v71, v0
	v_mov_b32_e32 v72, v0
	v_mov_b32_e32 v73, v0
	v_mov_b32_e32 v74, v0
	v_mov_b32_e32 v75, v0
	v_mov_b32_e32 v80, v0
	v_mov_b32_e32 v81, v0
	v_mov_b32_e32 v82, v0
	v_mov_b32_e32 v83, v0
	v_mov_b32_e32 v88, v0
	v_mov_b32_e32 v89, v0
	v_mov_b32_e32 v90, v0
	v_mov_b32_e32 v91, v0
	v_mov_b32_e32 v96, v0
	v_mov_b32_e32 v97, v0
	v_mov_b32_e32 v98, v0
	v_mov_b32_e32 v99, v0
	v_mov_b32_e32 v104, v0
	v_mov_b32_e32 v105, v0
	v_mov_b32_e32 v106, v0
	v_mov_b32_e32 v107, v0
	v_mov_b32_e32 v112, v0
	v_mov_b32_e32 v113, v0
	v_mov_b32_e32 v114, v0
	v_mov_b32_e32 v115, v0
	v_mov_b32_e32 v76, v0
	v_mov_b32_e32 v77, v0
	v_mov_b32_e32 v78, v0
	v_mov_b32_e32 v79, v0
	v_mov_b32_e32 v84, v0
	v_mov_b32_e32 v85, v0
	v_mov_b32_e32 v86, v0
	v_mov_b32_e32 v87, v0
	v_mov_b32_e32 v92, v0
	v_mov_b32_e32 v93, v0
	v_mov_b32_e32 v94, v0
	v_mov_b32_e32 v95, v0
	v_mov_b32_e32 v100, v0
	v_mov_b32_e32 v101, v0
	v_mov_b32_e32 v102, v0
	v_mov_b32_e32 v103, v0
	v_mov_b32_e32 v108, v0
	v_mov_b32_e32 v109, v0
	v_mov_b32_e32 v110, v0
	v_mov_b32_e32 v111, v0
	v_mov_b32_e32 v116, v0
	v_mov_b32_e32 v117, v0
	v_mov_b32_e32 v118, v0
	v_mov_b32_e32 v119, v0
	v_mov_b32_e32 v120, v0
	v_mov_b32_e32 v121, v0
	v_mov_b32_e32 v122, v0
	v_mov_b32_e32 v123, v0
	v_mov_b32_e32 v124, v0
	v_mov_b32_e32 v125, v0
	v_mov_b32_e32 v126, v0
	v_mov_b32_e32 v127, v0
	.p2align	6

; template <class Epi, class Sched, bool ALIGN_EPI = true, bool SP2 = true>
; __device__ __forceinline__ void gemm_phase(LAS unsigned char* lds, const bf16_t* Ag, const bf16_t* Btg, const int K, const int lda, const int ldb, const Sched& S, const Epi& E) {
;     ...
;         const bool has_next = S.next(ui + 1, nxt);
;         const char* nA = has_next ? (const char*)Ag + nxt.aoff : cA; const char* nB = has_next ? (const char*)Btg + nxt.boff : cB;
;     ...
; #pragma unroll
;         for (int a = 0; a < 2; ++a)
; #pragma unroll
;             for (int b = 0; b < 2; ++b)
; #pragma unroll
;                 for (int m = 0; m < 4; ++m)
; #pragma unroll
;                     for (int n = 0; n < 2; ++n) acc[a][b][m][n] = (f32x4){0.f, 0.f, 0.f, 0.f};
;         cur = nxt; cA = nA; cB = nB; ++ui;
.LBB0_1049:
	v_readlane_b32 s14, v245, 45
	v_readlane_b32 s15, v245, 46
	s_add_u32 s14, s14, s45
	s_addc_u32 s15, s15, s1
	s_and_b64 s[16:17], s[24:25], exec
	s_cselect_b32 s46, s15, s21
	s_cselect_b32 s47, s14, s20
	s_add_u32 s16, s56, s8
	s_addc_u32 s17, s57, s9
	s_and_b64 s[24:25], s[24:25], exec
	s_cselect_b32 s50, s17, s23
	s_cselect_b32 s51, s16, s22
	s_add_u32 s20, s20, 0x80080
	s_addc_u32 s21, s21, 0
	s_add_u32 s52, s22, 0x100
	v_mov_b32_e32 v0, 0
	s_addc_u32 s53, s23, 0
	s_mov_b32 s54, -2
	v_mov_b32_e32 v1, v0
	v_mov_b32_e32 v2, v0
	v_mov_b32_e32 v3, v0
	v_mov_b32_e32 v4, v0
	v_mov_b32_e32 v5, v0
	v_mov_b32_e32 v6, v0
	v_mov_b32_e32 v7, v0
	v_mov_b32_e32 v8, v0
	v_mov_b32_e32 v9, v0
	v_mov_b32_e32 v10, v0
	v_mov_b32_e32 v11, v0
	v_mov_b32_e32 v12, v0
	v_mov_b32_e32 v13, v0
	v_mov_b32_e32 v14, v0
	v_mov_b32_e32 v15, v0
	v_mov_b32_e32 v24, v0
	v_mov_b32_e32 v25, v0
	v_mov_b32_e32 v26, v0
	v_mov_b32_e32 v27, v0
	v_mov_b32_e32 v28, v0
	v_mov_b32_e32 v29, v0
	v_mov_b32_e32 v30, v0
	v_mov_b32_e32 v31, v0
	v_mov_b32_e32 v40, v0
	v_mov_b32_e32 v41, v0
	v_mov_b32_e32 v42, v0
	v_mov_b32_e32 v43, v0
	v_mov_b32_e32 v44, v0
	v_mov_b32_e32 v45, v0
	v_mov_b32_e32 v46, v0
	v_mov_b32_e32 v47, v0
	v_mov_b32_e32 v16, v0
	v_mov_b32_e32 v17, v0
	v_mov_b32_e32 v18, v0
	v_mov_b32_e32 v19, v0
	v_mov_b32_e32 v20, v0
	v_mov_b32_e32 v21, v0
	v_mov_b32_e32 v22, v0
	v_mov_b32_e32 v23, v0
	v_mov_b32_e32 v32, v0
	v_mov_b32_e32 v33, v0
	v_mov_b32_e32 v34, v0
	v_mov_b32_e32 v35, v0
	v_mov_b32_e32 v36, v0
	v_mov_b32_e32 v37, v0
	v_mov_b32_e32 v38, v0
	v_mov_b32_e32 v39, v0
	v_mov_b32_e32 v48, v0
	v_mov_b32_e32 v49, v0
	v_mov_b32_e32 v50, v0
	v_mov_b32_e32 v51, v0
	v_mov_b32_e32 v52, v0
	v_mov_b32_e32 v53, v0
	v_mov_b32_e32 v54, v0
	v_mov_b32_e32 v55, v0
	v_mov_b32_e32 v56, v0
	v_mov_b32_e32 v57, v0
	v_mov_b32_e32 v58, v0
	v_mov_b32_e32 v59, v0
	v_mov_b32_e32 v60, v0
	v_mov_b32_e32 v61, v0
	v_mov_b32_e32 v62, v0
	v_mov_b32_e32 v63, v0
	v_mov_b32_e32 v64, v0
	v_mov_b32_e32 v65, v0
	v_mov_b32_e32 v66, v0
	v_mov_b32_e32 v67, v0
	v_mov_b32_e32 v68, v0
	v_mov_b32_e32 v69, v0
	v_mov_b32_e32 v70, v0
	v_mov_b32_e32 v71, v0
	v_mov_b32_e32 v72, v0
	v_mov_b32_e32 v73, v0
	v_mov_b32_e32 v74, v0
	v_mov_b32_e32 v75, v0
	v_mov_b32_e32 v76, v0
	v_mov_b32_e32 v77, v0
	v_mov_b32_e32 v78, v0
	v_mov_b32_e32 v79, v0
	v_mov_b32_e32 v88, v0
	v_mov_b32_e32 v89, v0
	v_mov_b32_e32 v90, v0
	v_mov_b32_e32 v91, v0
	v_mov_b32_e32 v92, v0
	v_mov_b32_e32 v93, v0
	v_mov_b32_e32 v94, v0
	v_mov_b32_e32 v95, v0
	v_mov_b32_e32 v104, v0
	v_mov_b32_e32 v105, v0
	v_mov_b32_e32 v106, v0
	v_mov_b32_e32 v107, v0
	v_mov_b32_e32 v108, v0
	v_mov_b32_e32 v109, v0
	v_mov_b32_e32 v110, v0
	v_mov_b32_e32 v111, v0
	v_mov_b32_e32 v80, v0
	v_mov_b32_e32 v81, v0
	v_mov_b32_e32 v82, v0
	v_mov_b32_e32 v83, v0
	v_mov_b32_e32 v84, v0
	v_mov_b32_e32 v85, v0
	v_mov_b32_e32 v86, v0
	v_mov_b32_e32 v87, v0
	v_mov_b32_e32 v96, v0
	v_mov_b32_e32 v97, v0
	v_mov_b32_e32 v98, v0
	v_mov_b32_e32 v99, v0
	v_mov_b32_e32 v100, v0
	v_mov_b32_e32 v101, v0
	v_mov_b32_e32 v102, v0
	v_mov_b32_e32 v103, v0
	v_mov_b32_e32 v112, v0
	v_mov_b32_e32 v113, v0
	v_mov_b32_e32 v114, v0
	v_mov_b32_e32 v115, v0
	v_mov_b32_e32 v116, v0
	v_mov_b32_e32 v117, v0
	v_mov_b32_e32 v118, v0
	v_mov_b32_e32 v119, v0
	v_mov_b32_e32 v120, v0
	v_mov_b32_e32 v121, v0
	v_mov_b32_e32 v122, v0
	v_mov_b32_e32 v123, v0
	v_mov_b32_e32 v124, v0
	v_mov_b32_e32 v125, v0
	v_mov_b32_e32 v126, v0
	v_mov_b32_e32 v127, v0
	.p2align	6

; template <class Epi, class Sched, bool ALIGN_EPI = true, bool SP2 = true>
; __device__ __forceinline__ void gemm_phase(LAS unsigned char* lds, const bf16_t* Ag, const bf16_t* Btg, const int K, const int lda, const int ldb, const Sched& S, const Epi& E) {
;     ...
;         const bool has_next = S.next(ui + 1, nxt);
;         const char* nA = has_next ? (const char*)Ag + nxt.aoff : cA; const char* nB = has_next ? (const char*)Btg + nxt.boff : cB;
;     ...
; #pragma unroll
;         for (int a = 0; a < 2; ++a)
; #pragma unroll
;             for (int b = 0; b < 2; ++b)
; #pragma unroll
;                 for (int m = 0; m < 4; ++m)
; #pragma unroll
;                     for (int n = 0; n < 2; ++n) acc[a][b][m][n] = (f32x4){0.f, 0.f, 0.f, 0.f};
;         cur = nxt; cA = nA; cB = nB; ++ui;
.LBB0_1127:
	s_add_u32 s18, s80, s10
	s_addc_u32 s19, s81, s11
	s_and_b64 s[20:21], s[28:29], exec
	s_cselect_b32 s33, s19, s25
	s_cselect_b32 s53, s18, s24
	s_add_u32 s20, s62, s14
	s_addc_u32 s21, s63, s15
	s_and_b64 s[28:29], s[28:29], exec
	s_cselect_b32 s54, s21, s27
	s_cselect_b32 s55, s20, s26
	s_add_u32 s24, s24, 0x80080
	s_addc_u32 s25, s25, 0
	s_add_u32 s58, s26, 0x100
	v_mov_b32_e32 v0, 0
	s_addc_u32 s59, s27, 0
	s_mov_b32 s60, -2
	v_mov_b32_e32 v1, v0
	v_mov_b32_e32 v2, v0
	v_mov_b32_e32 v3, v0
	v_mov_b32_e32 v4, v0
	v_mov_b32_e32 v5, v0
	v_mov_b32_e32 v6, v0
	v_mov_b32_e32 v7, v0
	v_mov_b32_e32 v16, v0
	v_mov_b32_e32 v17, v0
	v_mov_b32_e32 v18, v0
	v_mov_b32_e32 v19, v0
	v_mov_b32_e32 v20, v0
	v_mov_b32_e32 v21, v0
	v_mov_b32_e32 v22, v0
	v_mov_b32_e32 v23, v0
	v_mov_b32_e32 v32, v0
	v_mov_b32_e32 v33, v0
	v_mov_b32_e32 v34, v0
	v_mov_b32_e32 v35, v0
	v_mov_b32_e32 v36, v0
	v_mov_b32_e32 v37, v0
	v_mov_b32_e32 v38, v0
	v_mov_b32_e32 v39, v0
	v_mov_b32_e32 v48, v0
	v_mov_b32_e32 v49, v0
	v_mov_b32_e32 v50, v0
	v_mov_b32_e32 v51, v0
	v_mov_b32_e32 v52, v0
	v_mov_b32_e32 v53, v0
	v_mov_b32_e32 v54, v0
	v_mov_b32_e32 v55, v0
	v_mov_b32_e32 v8, v0
	v_mov_b32_e32 v9, v0
	v_mov_b32_e32 v10, v0
	v_mov_b32_e32 v11, v0
	v_mov_b32_e32 v12, v0
	v_mov_b32_e32 v13, v0
	v_mov_b32_e32 v14, v0
	v_mov_b32_e32 v15, v0
	v_mov_b32_e32 v24, v0
	v_mov_b32_e32 v25, v0
	v_mov_b32_e32 v26, v0
	v_mov_b32_e32 v27, v0
	v_mov_b32_e32 v28, v0
	v_mov_b32_e32 v29, v0
	v_mov_b32_e32 v30, v0
	v_mov_b32_e32 v31, v0
	v_mov_b32_e32 v40, v0
	v_mov_b32_e32 v41, v0
	v_mov_b32_e32 v42, v0
	v_mov_b32_e32 v43, v0
	v_mov_b32_e32 v44, v0
	v_mov_b32_e32 v45, v0
	v_mov_b32_e32 v46, v0
	v_mov_b32_e32 v47, v0
	v_mov_b32_e32 v56, v0
	v_mov_b32_e32 v57, v0
	v_mov_b32_e32 v58, v0
	v_mov_b32_e32 v59, v0
	v_mov_b32_e32 v60, v0
	v_mov_b32_e32 v61, v0
	v_mov_b32_e32 v62, v0
	v_mov_b32_e32 v63, v0
	v_mov_b32_e32 v64, v0
	v_mov_b32_e32 v65, v0
	v_mov_b32_e32 v66, v0
	v_mov_b32_e32 v67, v0
	v_mov_b32_e32 v68, v0
	v_mov_b32_e32 v69, v0
	v_mov_b32_e32 v70, v0
	v_mov_b32_e32 v71, v0
	v_mov_b32_e32 v80, v0
	v_mov_b32_e32 v81, v0
	v_mov_b32_e32 v82, v0
	v_mov_b32_e32 v83, v0
	v_mov_b32_e32 v84, v0
	v_mov_b32_e32 v85, v0
	v_mov_b32_e32 v86, v0
	v_mov_b32_e32 v87, v0
	v_mov_b32_e32 v96, v0
	v_mov_b32_e32 v97, v0
	v_mov_b32_e32 v98, v0
	v_mov_b32_e32 v99, v0
	v_mov_b32_e32 v100, v0
	v_mov_b32_e32 v101, v0
	v_mov_b32_e32 v102, v0
	v_mov_b32_e32 v103, v0
	v_mov_b32_e32 v112, v0
	v_mov_b32_e32 v113, v0
	v_mov_b32_e32 v114, v0
	v_mov_b32_e32 v115, v0
	v_mov_b32_e32 v116, v0
	v_mov_b32_e32 v117, v0
	v_mov_b32_e32 v118, v0
	v_mov_b32_e32 v119, v0
	v_mov_b32_e32 v72, v0
	v_mov_b32_e32 v73, v0
	v_mov_b32_e32 v74, v0
	v_mov_b32_e32 v75, v0
	v_mov_b32_e32 v76, v0
	v_mov_b32_e32 v77, v0
	v_mov_b32_e32 v78, v0
	v_mov_b32_e32 v79, v0
	v_mov_b32_e32 v88, v0
	v_mov_b32_e32 v89, v0
	v_mov_b32_e32 v90, v0
	v_mov_b32_e32 v91, v0
	v_mov_b32_e32 v92, v0
	v_mov_b32_e32 v93, v0
	v_mov_b32_e32 v94, v0
	v_mov_b32_e32 v95, v0
	v_mov_b32_e32 v104, v0
	v_mov_b32_e32 v105, v0
	v_mov_b32_e32 v106, v0
	v_mov_b32_e32 v107, v0
	v_mov_b32_e32 v108, v0
	v_mov_b32_e32 v109, v0
	v_mov_b32_e32 v110, v0
	v_mov_b32_e32 v111, v0
	v_mov_b32_e32 v120, v0
	v_mov_b32_e32 v121, v0
	v_mov_b32_e32 v122, v0
	v_mov_b32_e32 v123, v0
	v_mov_b32_e32 v124, v0
	v_mov_b32_e32 v125, v0
	v_mov_b32_e32 v126, v0
	v_mov_b32_e32 v127, v0
	.p2align	6

; template <class Epi, class Sched, bool ALIGN_EPI = true, bool SP2 = true>
; __device__ __forceinline__ void gemm_phase(LAS unsigned char* lds, const bf16_t* Ag, const bf16_t* Btg, const int K, const int lda, const int ldb, const Sched& S, const Epi& E) {
;     ...
;         const bool has_next = S.next(ui + 1, nxt);
;         const char* nA = has_next ? (const char*)Ag + nxt.aoff : cA; const char* nB = has_next ? (const char*)Btg + nxt.boff : cB;
;     ...
; #pragma unroll
;         for (int a = 0; a < 2; ++a)
; #pragma unroll
;             for (int b = 0; b < 2; ++b)
; #pragma unroll
;                 for (int m = 0; m < 4; ++m)
; #pragma unroll
;                     for (int n = 0; n < 2; ++n) acc[a][b][m][n] = (f32x4){0.f, 0.f, 0.f, 0.f};
;         cur = nxt; cA = nA; cB = nB; ++ui;
.LBB0_1235:
	s_add_u32 s30, s96, s24
	s_addc_u32 s31, s97, s25
	s_and_b64 s[34:35], s[2:3], exec
	s_cselect_b32 s33, s31, s43
	s_cselect_b32 s65, s30, s42
	s_add_u32 s34, s4, s28
	s_addc_u32 s35, s5, s29
	s_and_b64 s[50:51], s[2:3], exec
	s_cselect_b32 s66, s35, s45
	s_cselect_b32 s67, s34, s44
	s_add_u32 s42, s42, 0x40080
	s_addc_u32 s43, s43, 0
	s_add_u32 s68, s44, 0x100
	v_mov_b32_e32 v0, 0
	s_addc_u32 s69, s45, 0
	s_mov_b32 s70, -2
	v_mov_b32_e32 v1, v0
	v_mov_b32_e32 v2, v0
	v_mov_b32_e32 v3, v0
	v_mov_b32_e32 v4, v0
	v_mov_b32_e32 v5, v0
	v_mov_b32_e32 v6, v0
	v_mov_b32_e32 v7, v0
	v_mov_b32_e32 v16, v0
	v_mov_b32_e32 v17, v0
	v_mov_b32_e32 v18, v0
	v_mov_b32_e32 v19, v0
	v_mov_b32_e32 v20, v0
	v_mov_b32_e32 v21, v0
	v_mov_b32_e32 v22, v0
	v_mov_b32_e32 v23, v0
	v_mov_b32_e32 v32, v0
	v_mov_b32_e32 v33, v0
	v_mov_b32_e32 v34, v0
	v_mov_b32_e32 v35, v0
	v_mov_b32_e32 v36, v0
	v_mov_b32_e32 v37, v0
	v_mov_b32_e32 v38, v0
	v_mov_b32_e32 v39, v0
	v_mov_b32_e32 v48, v0
	v_mov_b32_e32 v49, v0
	v_mov_b32_e32 v50, v0
	v_mov_b32_e32 v51, v0
	v_mov_b32_e32 v52, v0
	v_mov_b32_e32 v53, v0
	v_mov_b32_e32 v54, v0
	v_mov_b32_e32 v55, v0
	v_mov_b32_e32 v8, v0
	v_mov_b32_e32 v9, v0
	v_mov_b32_e32 v10, v0
	v_mov_b32_e32 v11, v0
	v_mov_b32_e32 v12, v0
	v_mov_b32_e32 v13, v0
	v_mov_b32_e32 v14, v0
	v_mov_b32_e32 v15, v0
	v_mov_b32_e32 v24, v0
	v_mov_b32_e32 v25, v0
	v_mov_b32_e32 v26, v0
	v_mov_b32_e32 v27, v0
	v_mov_b32_e32 v28, v0
	v_mov_b32_e32 v29, v0
	v_mov_b32_e32 v30, v0
	v_mov_b32_e32 v31, v0
	v_mov_b32_e32 v40, v0
	v_mov_b32_e32 v41, v0
	v_mov_b32_e32 v42, v0
	v_mov_b32_e32 v43, v0
	v_mov_b32_e32 v44, v0
	v_mov_b32_e32 v45, v0
	v_mov_b32_e32 v46, v0
	v_mov_b32_e32 v47, v0
	v_mov_b32_e32 v56, v0
	v_mov_b32_e32 v57, v0
	v_mov_b32_e32 v58, v0
	v_mov_b32_e32 v59, v0
	v_mov_b32_e32 v60, v0
	v_mov_b32_e32 v61, v0
	v_mov_b32_e32 v62, v0
	v_mov_b32_e32 v63, v0
	v_mov_b32_e32 v64, v0
	v_mov_b32_e32 v65, v0
	v_mov_b32_e32 v66, v0
	v_mov_b32_e32 v67, v0
	v_mov_b32_e32 v68, v0
	v_mov_b32_e32 v69, v0
	v_mov_b32_e32 v70, v0
	v_mov_b32_e32 v71, v0
	v_mov_b32_e32 v80, v0
	v_mov_b32_e32 v81, v0
	v_mov_b32_e32 v82, v0
	v_mov_b32_e32 v83, v0
	v_mov_b32_e32 v84, v0
	v_mov_b32_e32 v85, v0
	v_mov_b32_e32 v86, v0
	v_mov_b32_e32 v87, v0
	v_mov_b32_e32 v96, v0
	v_mov_b32_e32 v97, v0
	v_mov_b32_e32 v98, v0
	v_mov_b32_e32 v99, v0
	v_mov_b32_e32 v100, v0
	v_mov_b32_e32 v101, v0
	v_mov_b32_e32 v102, v0
	v_mov_b32_e32 v103, v0
	v_mov_b32_e32 v104, v0
	v_mov_b32_e32 v105, v0
	v_mov_b32_e32 v106, v0
	v_mov_b32_e32 v107, v0
	v_mov_b32_e32 v112, v0
	v_mov_b32_e32 v113, v0
	v_mov_b32_e32 v114, v0
	v_mov_b32_e32 v115, v0
	v_mov_b32_e32 v72, v0
	v_mov_b32_e32 v73, v0
	v_mov_b32_e32 v74, v0
	v_mov_b32_e32 v75, v0
	v_mov_b32_e32 v76, v0
	v_mov_b32_e32 v77, v0
	v_mov_b32_e32 v78, v0
	v_mov_b32_e32 v79, v0
	v_mov_b32_e32 v88, v0
	v_mov_b32_e32 v89, v0
	v_mov_b32_e32 v90, v0
	v_mov_b32_e32 v91, v0
	v_mov_b32_e32 v92, v0
	v_mov_b32_e32 v93, v0
	v_mov_b32_e32 v94, v0
	v_mov_b32_e32 v95, v0
	v_mov_b32_e32 v108, v0
	v_mov_b32_e32 v109, v0
	v_mov_b32_e32 v110, v0
	v_mov_b32_e32 v111, v0
	v_mov_b32_e32 v116, v0
	v_mov_b32_e32 v117, v0
	v_mov_b32_e32 v118, v0
	v_mov_b32_e32 v119, v0
	v_mov_b32_e32 v120, v0
	v_mov_b32_e32 v121, v0
	v_mov_b32_e32 v122, v0
	v_mov_b32_e32 v123, v0
	v_mov_b32_e32 v124, v0
	v_mov_b32_e32 v125, v0
	v_mov_b32_e32 v126, v0
	v_mov_b32_e32 v127, v0
	.p2align	6

; template <class Epi, class Sched, bool ALIGN_EPI = true, bool SP2 = true>
; __device__ __forceinline__ void gemm_phase(LAS unsigned char* lds, const bf16_t* Ag, const bf16_t* Btg, const int K, const int lda, const int ldb, const Sched& S, const Epi& E) {
;     ...
;         const bool has_next = S.next(ui + 1, nxt);
;         const char* nA = has_next ? (const char*)Ag + nxt.aoff : cA; const char* nB = has_next ? (const char*)Btg + nxt.boff : cB;
;     ...
; #pragma unroll
;         for (int a = 0; a < 2; ++a)
; #pragma unroll
;             for (int b = 0; b < 2; ++b)
; #pragma unroll
;                 for (int m = 0; m < 4; ++m)
; #pragma unroll
;                     for (int n = 0; n < 2; ++n) acc[a][b][m][n] = (f32x4){0.f, 0.f, 0.f, 0.f};
;         cur = nxt; cA = nA; cB = nB; ++ui;
.LBB0_1368:
	s_add_u32 s18, s80, s12
	s_addc_u32 s19, s81, s13
	s_and_b64 s[20:21], s[2:3], exec
	s_cselect_b32 s52, s19, s25
	s_cselect_b32 s53, s18, s24
	s_add_u32 s20, s48, s14
	s_addc_u32 s21, s49, s15
	s_and_b64 s[28:29], s[2:3], exec
	s_cselect_b32 s54, s21, s27
	s_cselect_b32 s55, s20, s26
	s_add_u32 s24, s24, 0x80080
	s_addc_u32 s25, s25, 0
	s_add_u32 s56, s26, 0x100
	v_mov_b32_e32 v0, 0
	s_addc_u32 s57, s27, 0
	s_mov_b32 s58, -2
	v_mov_b32_e32 v1, v0
	v_mov_b32_e32 v2, v0
	v_mov_b32_e32 v3, v0
	v_mov_b32_e32 v4, v0
	v_mov_b32_e32 v5, v0
	v_mov_b32_e32 v6, v0
	v_mov_b32_e32 v7, v0
	v_mov_b32_e32 v16, v0
	v_mov_b32_e32 v17, v0
	v_mov_b32_e32 v18, v0
	v_mov_b32_e32 v19, v0
	v_mov_b32_e32 v20, v0
	v_mov_b32_e32 v21, v0
	v_mov_b32_e32 v22, v0
	v_mov_b32_e32 v23, v0
	v_mov_b32_e32 v32, v0
	v_mov_b32_e32 v33, v0
	v_mov_b32_e32 v34, v0
	v_mov_b32_e32 v35, v0
	v_mov_b32_e32 v36, v0
	v_mov_b32_e32 v37, v0
	v_mov_b32_e32 v38, v0
	v_mov_b32_e32 v39, v0
	v_mov_b32_e32 v48, v0
	v_mov_b32_e32 v49, v0
	v_mov_b32_e32 v50, v0
	v_mov_b32_e32 v51, v0
	v_mov_b32_e32 v52, v0
	v_mov_b32_e32 v53, v0
	v_mov_b32_e32 v54, v0
	v_mov_b32_e32 v55, v0
	v_mov_b32_e32 v8, v0
	v_mov_b32_e32 v9, v0
	v_mov_b32_e32 v10, v0
	v_mov_b32_e32 v11, v0
	v_mov_b32_e32 v12, v0
	v_mov_b32_e32 v13, v0
	v_mov_b32_e32 v14, v0
	v_mov_b32_e32 v15, v0
	v_mov_b32_e32 v24, v0
	v_mov_b32_e32 v25, v0
	v_mov_b32_e32 v26, v0
	v_mov_b32_e32 v27, v0
	v_mov_b32_e32 v28, v0
	v_mov_b32_e32 v29, v0
	v_mov_b32_e32 v30, v0
	v_mov_b32_e32 v31, v0
	v_mov_b32_e32 v40, v0
	v_mov_b32_e32 v41, v0
	v_mov_b32_e32 v42, v0
	v_mov_b32_e32 v43, v0
	v_mov_b32_e32 v44, v0
	v_mov_b32_e32 v45, v0
	v_mov_b32_e32 v46, v0
	v_mov_b32_e32 v47, v0
	v_mov_b32_e32 v56, v0
	v_mov_b32_e32 v57, v0
	v_mov_b32_e32 v58, v0
	v_mov_b32_e32 v59, v0
	v_mov_b32_e32 v60, v0
	v_mov_b32_e32 v61, v0
	v_mov_b32_e32 v62, v0
	v_mov_b32_e32 v63, v0
	v_mov_b32_e32 v64, v0
	v_mov_b32_e32 v65, v0
	v_mov_b32_e32 v66, v0
	v_mov_b32_e32 v67, v0
	v_mov_b32_e32 v68, v0
	v_mov_b32_e32 v69, v0
	v_mov_b32_e32 v70, v0
	v_mov_b32_e32 v71, v0
	v_mov_b32_e32 v80, v0
	v_mov_b32_e32 v81, v0
	v_mov_b32_e32 v82, v0
	v_mov_b32_e32 v83, v0
	v_mov_b32_e32 v84, v0
	v_mov_b32_e32 v85, v0
	v_mov_b32_e32 v86, v0
	v_mov_b32_e32 v87, v0
	v_mov_b32_e32 v96, v0
	v_mov_b32_e32 v97, v0
	v_mov_b32_e32 v98, v0
	v_mov_b32_e32 v99, v0
	v_mov_b32_e32 v100, v0
	v_mov_b32_e32 v101, v0
	v_mov_b32_e32 v102, v0
	v_mov_b32_e32 v103, v0
	v_mov_b32_e32 v112, v0
	v_mov_b32_e32 v113, v0
	v_mov_b32_e32 v114, v0
	v_mov_b32_e32 v115, v0
	v_mov_b32_e32 v116, v0
	v_mov_b32_e32 v117, v0
	v_mov_b32_e32 v118, v0
	v_mov_b32_e32 v119, v0
	v_mov_b32_e32 v72, v0
	v_mov_b32_e32 v73, v0
	v_mov_b32_e32 v74, v0
	v_mov_b32_e32 v75, v0
	v_mov_b32_e32 v76, v0
	v_mov_b32_e32 v77, v0
	v_mov_b32_e32 v78, v0
	v_mov_b32_e32 v79, v0
	v_mov_b32_e32 v88, v0
	v_mov_b32_e32 v89, v0
	v_mov_b32_e32 v90, v0
	v_mov_b32_e32 v91, v0
	v_mov_b32_e32 v92, v0
	v_mov_b32_e32 v93, v0
	v_mov_b32_e32 v94, v0
	v_mov_b32_e32 v95, v0
	v_mov_b32_e32 v104, v0
	v_mov_b32_e32 v105, v0
	v_mov_b32_e32 v106, v0
	v_mov_b32_e32 v107, v0
	v_mov_b32_e32 v108, v0
	v_mov_b32_e32 v109, v0
	v_mov_b32_e32 v110, v0
	v_mov_b32_e32 v111, v0
	v_mov_b32_e32 v120, v0
	v_mov_b32_e32 v121, v0
	v_mov_b32_e32 v122, v0
	v_mov_b32_e32 v123, v0
	v_mov_b32_e32 v124, v0
	v_mov_b32_e32 v125, v0
	v_mov_b32_e32 v126, v0
	v_mov_b32_e32 v127, v0
	.p2align	6

; template <class Epi, class Sched, bool ALIGN_EPI = true, bool SP2 = true>
; __device__ __forceinline__ void gemm_phase(LAS unsigned char* lds, const bf16_t* Ag, const bf16_t* Btg, const int K, const int lda, const int ldb, const Sched& S, const Epi& E) {
;     ...
;         const bool has_next = S.next(ui + 1, nxt);
;         const char* nA = has_next ? (const char*)Ag + nxt.aoff : cA; const char* nB = has_next ? (const char*)Btg + nxt.boff : cB;
;     ...
; #pragma unroll
;         for (int a = 0; a < 2; ++a)
; #pragma unroll
;             for (int b = 0; b < 2; ++b)
; #pragma unroll
;                 for (int m = 0; m < 4; ++m)
; #pragma unroll
;                     for (int n = 0; n < 2; ++n) acc[a][b][m][n] = (f32x4){0.f, 0.f, 0.f, 0.f};
;         cur = nxt; cA = nA; cB = nB; ++ui;
.LBB0_1447:
	v_readlane_b32 s44, v244, 11
	v_readlane_b32 s45, v244, 12
	s_add_u32 s44, s44, s34
	s_addc_u32 s45, s45, s35
	s_and_b64 s[46:47], s[2:3], exec
	v_readlane_b32 s46, v245, 47
	s_cselect_b32 s33, s45, s53
	s_cselect_b32 s74, s44, s52
	v_readlane_b32 s47, v245, 48
	s_add_u32 s46, s46, s38
	s_addc_u32 s47, s47, s39
	s_and_b64 s[56:57], s[2:3], exec
	s_cselect_b32 s75, s47, s55
	s_cselect_b32 s76, s46, s54
	s_add_u32 s52, s52, 0x160080
	s_addc_u32 s53, s53, 0
	s_add_u32 s77, s54, 0x100
	v_mov_b32_e32 v0, 0
	s_addc_u32 s78, s55, 0
	s_mov_b32 s79, -2
	v_mov_b32_e32 v1, v0
	v_mov_b32_e32 v2, v0
	v_mov_b32_e32 v3, v0
	v_mov_b32_e32 v4, v0
	v_mov_b32_e32 v5, v0
	v_mov_b32_e32 v6, v0
	v_mov_b32_e32 v7, v0
	v_mov_b32_e32 v16, v0
	v_mov_b32_e32 v17, v0
	v_mov_b32_e32 v18, v0
	v_mov_b32_e32 v19, v0
	v_mov_b32_e32 v20, v0
	v_mov_b32_e32 v21, v0
	v_mov_b32_e32 v22, v0
	v_mov_b32_e32 v23, v0
	v_mov_b32_e32 v32, v0
	v_mov_b32_e32 v33, v0
	v_mov_b32_e32 v34, v0
	v_mov_b32_e32 v35, v0
	v_mov_b32_e32 v36, v0
	v_mov_b32_e32 v37, v0
	v_mov_b32_e32 v38, v0
	v_mov_b32_e32 v39, v0
	v_mov_b32_e32 v48, v0
	v_mov_b32_e32 v49, v0
	v_mov_b32_e32 v50, v0
	v_mov_b32_e32 v51, v0
	v_mov_b32_e32 v52, v0
	v_mov_b32_e32 v53, v0
	v_mov_b32_e32 v54, v0
	v_mov_b32_e32 v55, v0
	v_mov_b32_e32 v8, v0
	v_mov_b32_e32 v9, v0
	v_mov_b32_e32 v10, v0
	v_mov_b32_e32 v11, v0
	v_mov_b32_e32 v12, v0
	v_mov_b32_e32 v13, v0
	v_mov_b32_e32 v14, v0
	v_mov_b32_e32 v15, v0
	v_mov_b32_e32 v24, v0
	v_mov_b32_e32 v25, v0
	v_mov_b32_e32 v26, v0
	v_mov_b32_e32 v27, v0
	v_mov_b32_e32 v28, v0
	v_mov_b32_e32 v29, v0
	v_mov_b32_e32 v30, v0
	v_mov_b32_e32 v31, v0
	v_mov_b32_e32 v40, v0
	v_mov_b32_e32 v41, v0
	v_mov_b32_e32 v42, v0
	v_mov_b32_e32 v43, v0
	v_mov_b32_e32 v44, v0
	v_mov_b32_e32 v45, v0
	v_mov_b32_e32 v46, v0
	v_mov_b32_e32 v47, v0
	v_mov_b32_e32 v56, v0
	v_mov_b32_e32 v57, v0
	v_mov_b32_e32 v58, v0
	v_mov_b32_e32 v59, v0
	v_mov_b32_e32 v60, v0
	v_mov_b32_e32 v61, v0
	v_mov_b32_e32 v62, v0
	v_mov_b32_e32 v63, v0
	v_mov_b32_e32 v64, v0
	v_mov_b32_e32 v65, v0
	v_mov_b32_e32 v66, v0
	v_mov_b32_e32 v67, v0
	v_mov_b32_e32 v68, v0
	v_mov_b32_e32 v69, v0
	v_mov_b32_e32 v70, v0
	v_mov_b32_e32 v71, v0
	v_mov_b32_e32 v80, v0
	v_mov_b32_e32 v81, v0
	v_mov_b32_e32 v82, v0
	v_mov_b32_e32 v83, v0
	v_mov_b32_e32 v84, v0
	v_mov_b32_e32 v85, v0
	v_mov_b32_e32 v86, v0
	v_mov_b32_e32 v87, v0
	v_mov_b32_e32 v96, v0
	v_mov_b32_e32 v97, v0
	v_mov_b32_e32 v98, v0
	v_mov_b32_e32 v99, v0
	v_mov_b32_e32 v100, v0
	v_mov_b32_e32 v101, v0
	v_mov_b32_e32 v102, v0
	v_mov_b32_e32 v103, v0
	v_mov_b32_e32 v112, v0
	v_mov_b32_e32 v113, v0
	v_mov_b32_e32 v114, v0
	v_mov_b32_e32 v115, v0
	v_mov_b32_e32 v116, v0
	v_mov_b32_e32 v117, v0
	v_mov_b32_e32 v118, v0
	v_mov_b32_e32 v119, v0
	v_mov_b32_e32 v72, v0
	v_mov_b32_e32 v73, v0
	v_mov_b32_e32 v74, v0
	v_mov_b32_e32 v75, v0
	v_mov_b32_e32 v76, v0
	v_mov_b32_e32 v77, v0
	v_mov_b32_e32 v78, v0
	v_mov_b32_e32 v79, v0
	v_mov_b32_e32 v88, v0
	v_mov_b32_e32 v89, v0
	v_mov_b32_e32 v90, v0
	v_mov_b32_e32 v91, v0
	v_mov_b32_e32 v92, v0
	v_mov_b32_e32 v93, v0
	v_mov_b32_e32 v94, v0
	v_mov_b32_e32 v95, v0
	v_mov_b32_e32 v104, v0
	v_mov_b32_e32 v105, v0
	v_mov_b32_e32 v106, v0
	v_mov_b32_e32 v107, v0
	v_mov_b32_e32 v108, v0
	v_mov_b32_e32 v109, v0
	v_mov_b32_e32 v110, v0
	v_mov_b32_e32 v111, v0
	v_mov_b32_e32 v120, v0
	v_mov_b32_e32 v121, v0
	v_mov_b32_e32 v122, v0
	v_mov_b32_e32 v123, v0
	v_mov_b32_e32 v124, v0
	v_mov_b32_e32 v125, v0
	v_mov_b32_e32 v126, v0
	v_mov_b32_e32 v127, v0
	.p2align	6
